# cache-policy experiment: prep output stores (W, QD, KDT, UT, ATT) issued without the nt hint so the scan's reads can hit MALL/L2
# baseline (speedup 1.0000x reference)
.LBB0_316:
	v_ashrrev_i32_e32 v181, 3, v135
	s_lshr_b32 s0, s23, 7
	v_and_b32_e32 v183, -2, v181
	v_and_b32_e32 v1, 15, v135
	s_lshl_b32 s0, s0, 6
	v_add3_u32 v60, s7, -3, v183
	v_lshlrev_b32_e32 v3, 3, v1
	s_and_b32 s0, s0, 0x180
	v_max_i32_e32 v16, -2, v60
	v_add_u32_e32 v62, s7, v183
	v_or_b32_e32 v61, s0, v3
	v_add_u32_e32 v16, 2, v16
	v_mov_b32_e32 v17, v0
	v_max_i32_e32 v20, 0, v62
	v_mov_b32_e32 v21, v0
	v_lshlrev_b32_e32 v28, 1, v61
	v_mov_b32_e32 v29, v0
	v_max_i32_e32 v12, -1, v60
	v_lshl_add_u64 v[16:17], s[4:5], 0, v[16:17]
	v_lshl_add_u64 v[20:21], s[4:5], 0, v[20:21]
	v_max_i32_e32 v26, -4, v60
	v_lshl_add_u64 v[24:25], s[12:13], 0, v[28:29]
	v_max_i32_e32 v8, 0, v60
	v_mov_b32_e32 v9, v0
	v_add_u32_e32 v12, 1, v12
	v_mov_b32_e32 v13, v0
	v_lshlrev_b64 v[36:37], 12, v[16:17]
	v_lshlrev_b64 v[40:41], 12, v[20:21]
	v_add_u32_e32 v26, 4, v26
	v_mov_b32_e32 v27, v0
	v_lshl_add_u64 v[8:9], s[4:5], 0, v[8:9]
	v_lshl_add_u64 v[12:13], s[4:5], 0, v[12:13]
	v_lshl_add_u64 v[16:17], v[24:25], 0, v[36:37]
	v_lshl_add_u64 v[20:21], v[24:25], 0, v[40:41]
	v_lshl_add_u64 v[26:27], s[4:5], 0, v[26:27]
	s_waitcnt lgkmcnt(0)
	s_barrier
	v_lshlrev_b64 v[30:31], 12, v[8:9]
	v_lshlrev_b64 v[32:33], 12, v[12:13]
	global_load_dwordx4 v[16:19], v[16:17], off
	v_lshlrev_b64 v[44:45], 12, v[26:27]
	global_load_dwordx4 v[20:23], v[20:21], off
	v_lshl_add_u64 v[8:9], v[24:25], 0, v[30:31]
	v_lshl_add_u64 v[12:13], v[24:25], 0, v[32:33]
	v_lshl_add_u64 v[24:25], v[24:25], 0, v[44:45]
	global_load_dwordx4 v[24:27], v[24:25], off
	v_mov_b32_e32 v47, v0
	global_load_dwordx4 v[8:11], v[8:9], off
	v_or_b32_e32 v46, 0x400, v28
	global_load_dwordx4 v[12:15], v[12:13], off
	v_lshl_add_u64 v[54:55], s[12:13], 0, v[40:41]
	v_lshl_add_u64 v[40:41], v[54:55], 0, v[46:47]
	v_lshl_add_u64 v[58:59], s[12:13], 0, v[44:45]
	v_lshl_add_u64 v[48:49], s[12:13], 0, v[30:31]
	v_lshl_add_u64 v[50:51], s[12:13], 0, v[32:33]
	v_lshl_add_u64 v[52:53], s[12:13], 0, v[36:37]
	global_load_dwordx4 v[40:43], v[40:41], off
	v_lshl_add_u64 v[44:45], v[58:59], 0, v[46:47]
	v_lshl_add_u64 v[28:29], v[48:49], 0, v[46:47]
	v_lshl_add_u64 v[32:33], v[50:51], 0, v[46:47]
	v_lshl_add_u64 v[36:37], v[52:53], 0, v[46:47]
	global_load_dwordx4 v[44:47], v[44:45], off
	v_cmp_gt_i32_e64 s[4:5], 0, v62
	v_readlane_b32 s34, v251, 51
	v_lshl_or_b32 v3, s6, 7, v3
	v_readlane_b32 s35, v251, 52
	v_or_b32_e32 v3, 0x400, v3
	v_cmp_gt_i32_e64 s[6:7], -4, v60
	global_load_dwordx4 v[28:31], v[28:29], off
	v_mov_b32_e32 v57, v0
	v_lshlrev_b32_e32 v56, 1, v3
	v_lshl_add_u64 v[48:49], v[48:49], 0, v[56:57]
	v_cmp_gt_i32_e32 vcc, 0, v60
	v_cmp_gt_i32_e64 s[0:1], -1, v60
	v_cmp_gt_i32_e64 s[2:3], -2, v60
	s_movk_i32 s25, 0x4000
	global_load_dwordx4 v[32:35], v[32:33], off
	v_lshl_add_u64 v[50:51], v[50:51], 0, v[56:57]
	global_load_dwordx4 v[36:39], v[36:37], off
	s_nop 0
	global_load_dwordx4 v[104:107], v[48:49], off
	global_load_dwordx4 v[108:111], v[50:51], off
	s_mov_b64 s[28:29], 0x2000
	s_movk_i32 s26, 0x6000
	s_mov_b64 s[30:31], 0x6000
	v_add_u32_e32 v201, 64, v2
	v_lshlrev_b32_e32 v197, 4, v1
	v_lshrrev_b32_e32 v198, 5, v135
	v_bfe_u32 v200, v135, 2, 2
	s_waitcnt vmcnt(11)
	v_cndmask_b32_e64 v161, v16, 0, s[2:3]
	v_cndmask_b32_e64 v129, v17, 0, s[2:3]
	s_waitcnt vmcnt(10)
	v_cndmask_b32_e64 v163, v20, 0, s[4:5]
	v_cndmask_b32_e64 v131, v21, 0, s[4:5]
	v_lshlrev_b32_e32 v20, 2, v61
	v_mov_b32_e32 v21, v0
	v_cndmask_b32_e64 v125, v22, 0, s[4:5]
	v_cndmask_b32_e64 v117, v23, 0, s[4:5]
	v_lshl_add_u64 v[22:23], s[34:35], 0, v[20:21]
	s_waitcnt vmcnt(9)
	v_cndmask_b32_e64 v202, v26, 0, s[6:7]
	v_add_co_u32_e64 v26, s[8:9], s62, v22
	v_cndmask_b32_e64 v203, v27, 0, s[6:7]
	s_nop 0
	v_addc_co_u32_e64 v27, s[8:9], 0, v23, s[8:9]
	s_waitcnt vmcnt(8)
	v_cndmask_b32_e64 v165, v8, 0, vcc
	v_cndmask_b32_e64 v118, v9, 0, vcc
	s_waitcnt vmcnt(7)
	v_cndmask_b32_e64 v133, v12, 0, s[0:1]
	v_cndmask_b32_e64 v127, v13, 0, s[0:1]
	v_lshl_add_u64 v[8:9], v[52:53], 0, v[56:57]
	v_lshl_add_u64 v[12:13], v[54:55], 0, v[56:57]
	v_lshl_add_u64 v[16:17], v[58:59], 0, v[56:57]
	v_add_co_u32_e64 v48, s[8:9], s25, v22
	v_cndmask_b32_e64 v119, v10, 0, vcc
	v_cndmask_b32_e64 v120, v11, 0, vcc
	v_cndmask_b32_e64 v121, v14, 0, s[0:1]
	v_cndmask_b32_e64 v113, v15, 0, s[0:1]
	v_cndmask_b32_e64 v123, v18, 0, s[2:3]
	v_cndmask_b32_e64 v115, v19, 0, s[2:3]
	global_load_dwordx4 v[8:11], v[8:9], off
	v_cndmask_b32_e64 v196, v24, 0, s[6:7]
	global_load_dwordx4 v[12:15], v[12:13], off
	v_cndmask_b32_e64 v199, v25, 0, s[6:7]
	global_load_dwordx4 v[16:19], v[16:17], off
	s_nop 0
	global_load_dwordx4 v[72:75], v20, s[34:35]
	global_load_dwordx4 v[88:91], v20, s[34:35] offset:16
	v_lshl_add_u64 v[24:25], v[22:23], 0, s[28:29]
	v_addc_co_u32_e64 v49, s[8:9], 0, v23, s[8:9]
	global_load_dwordx4 v[76:79], v[26:27], off
	global_load_dwordx4 v[92:95], v[24:25], off offset:16
	v_lshl_add_u64 v[24:25], v[22:23], 0, s[48:49]
	v_add_co_u32_e64 v52, s[8:9], s26, v22
	global_load_dwordx4 v[96:99], v[24:25], off offset:16
	s_nop 0
	v_addc_co_u32_e64 v53, s[8:9], 0, v23, s[8:9]
	v_lshl_add_u64 v[24:25], v[22:23], 0, s[30:31]
	global_load_dwordx4 v[80:83], v[52:53], off
	global_load_dwordx4 v[100:103], v[24:25], off offset:16
	s_mov_b64 s[8:9], 0x2800
	s_waitcnt vmcnt(16)
	v_cndmask_b32_e64 v180, v40, 0, s[4:5]
	v_cndmask_b32_e64 v187, v41, 0, s[4:5]
	v_cndmask_b32_e64 v191, v42, 0, s[4:5]
	v_cndmask_b32_e64 v195, v43, 0, s[4:5]
	global_load_dwordx4 v[40:43], v20, s[34:35] offset:2048
	global_load_dwordx4 v[56:59], v20, s[34:35] offset:2064
	v_lshl_add_u64 v[20:21], v[22:23], 0, s[8:9]
	s_mov_b64 s[8:9], 0x4800
	s_waitcnt vmcnt(17)
	v_cndmask_b32_e64 v172, v44, 0, s[6:7]
	v_cndmask_b32_e64 v174, v45, 0, s[6:7]
	v_cndmask_b32_e64 v175, v46, 0, s[6:7]
	v_cndmask_b32_e64 v176, v47, 0, s[6:7]
	global_load_dwordx4 v[44:47], v[26:27], off offset:2048
	v_lshl_add_u64 v[24:25], v[22:23], 0, s[8:9]
	global_load_dwordx4 v[84:87], v[48:49], off
	s_nop 0
	global_load_dwordx4 v[48:51], v[48:49], off offset:2048
	s_nop 0
	global_load_dwordx4 v[64:67], v[20:21], off offset:16
	global_load_dwordx4 v[68:71], v[24:25], off offset:16
	s_waitcnt vmcnt(18)
	v_cndmask_b32_e64 v148, v105, 0, vcc
	v_cndmask_b32_e64 v168, v104, 0, vcc
	v_lshlrev_b32_e32 v104, 16, v120
	v_and_b32_e32 v105, 0xffff0000, v120
	v_lshlrev_b32_e32 v112, 16, v113
	v_and_b32_e32 v113, 0xffff0000, v113
	v_lshlrev_b32_e32 v114, 16, v115
	v_and_b32_e32 v115, 0xffff0000, v115
	v_lshlrev_b32_e32 v116, 16, v117
	v_and_b32_e32 v117, 0xffff0000, v117
	s_mov_b64 s[8:9], 0x6800
	v_cndmask_b32_e64 v140, v107, 0, vcc
	v_lshl_add_u64 v[20:21], v[22:23], 0, s[8:9]
	v_cndmask_b32_e64 v144, v106, 0, vcc
	global_load_dwordx4 v[52:55], v[52:53], off offset:2048
	s_nop 0
	global_load_dwordx4 v[60:63], v[20:21], off offset:16
	v_cndmask_b32_e64 v177, v28, 0, vcc
	v_cndmask_b32_e64 v184, v29, 0, vcc
	v_cndmask_b32_e64 v188, v30, 0, vcc
	v_cndmask_b32_e64 v192, v31, 0, vcc
	v_cndmask_b32_e64 v178, v32, 0, s[0:1]
	v_cndmask_b32_e64 v185, v33, 0, s[0:1]
	v_cndmask_b32_e64 v189, v34, 0, s[0:1]
	v_cndmask_b32_e64 v193, v35, 0, s[0:1]
	s_waitcnt vmcnt(19)
	v_cndmask_b32_e64 v141, v111, 0, s[0:1]
	v_cndmask_b32_e64 v145, v110, 0, s[0:1]
	v_cndmask_b32_e64 v149, v109, 0, s[0:1]
	v_cndmask_b32_e64 v169, v108, 0, s[0:1]
	v_xor_b32_e32 v108, 1, v182
	v_lshlrev_b32_e32 v120, 16, v121
	v_and_b32_e32 v121, 0xffff0000, v121
	v_lshlrev_b32_e32 v122, 16, v123
	v_and_b32_e32 v123, 0xffff0000, v123
	v_lshlrev_b32_e32 v124, 16, v125
	v_and_b32_e32 v125, 0xffff0000, v125
	v_lshlrev_b32_e32 v130, 16, v131
	v_and_b32_e32 v131, 0xffff0000, v131
	v_cndmask_b32_e64 v179, v36, 0, s[2:3]
	v_cndmask_b32_e64 v186, v37, 0, s[2:3]
	v_cndmask_b32_e64 v190, v38, 0, s[2:3]
	v_cndmask_b32_e64 v194, v39, 0, s[2:3]
	s_waitcnt vmcnt(18)
	v_cndmask_b32_e64 v142, v11, 0, s[2:3]
	v_cndmask_b32_e64 v146, v10, 0, s[2:3]
	s_waitcnt vmcnt(17)
	v_cndmask_b32_e64 v171, v12, 0, s[4:5]
	v_lshlrev_b32_e32 v12, 2, v3
	v_cndmask_b32_e64 v151, v13, 0, s[4:5]
	s_waitcnt vmcnt(14)
	v_pk_fma_f32 v[104:105], v[90:91], v[104:105], 0 op_sel_hi:[1,1,0]
	v_mov_b32_e32 v13, v0
	v_lshl_add_u64 v[20:21], s[34:35], 0, v[12:13]
	v_cndmask_b32_e64 v147, v14, 0, s[4:5]
	s_waitcnt vmcnt(12)
	v_pk_fma_f32 v[104:105], v[94:95], v[112:113], v[104:105]
	v_add_co_u32_e32 v14, vcc, s62, v20
	v_cndmask_b32_e64 v143, v15, 0, s[4:5]
	s_waitcnt vmcnt(11)
	v_pk_fma_f32 v[104:105], v[98:99], v[114:115], v[104:105]
	v_addc_co_u32_e32 v15, vcc, 0, v21, vcc
	v_cndmask_b32_e64 v137, v18, 0, s[6:7]
	s_waitcnt vmcnt(9)
	v_pk_fma_f32 v[104:105], v[102:103], v[116:117], v[104:105]
	v_add_co_u32_e32 v18, vcc, s25, v20
	v_mul_f32_e32 v3, 0xbfb8aa3b, v105
	v_exp_f32_e32 v107, v3
	v_mul_f32_e32 v3, 0xbfb8aa3b, v104
	v_exp_f32_e32 v106, v3
	v_cndmask_b32_e64 v136, v19, 0, s[6:7]
	v_addc_co_u32_e32 v19, vcc, 0, v21, vcc
	v_pk_add_f32 v[2:3], v[106:107], 1.0 op_sel_hi:[1,0]
	v_cndmask_b32_e64 v150, v9, 0, s[2:3]
	s_nop 0
	v_cndmask_b32_e64 v170, v8, 0, s[2:3]
	v_cndmask_b32_e64 v138, v17, 0, s[6:7]
	v_cndmask_b32_e64 v139, v16, 0, s[6:7]
	global_load_dwordx4 v[8:11], v12, s[34:35] offset:16
	global_load_dwordx4 v[24:27], v12, s[34:35]
	v_lshl_add_u64 v[12:13], v[20:21], 0, s[28:29]
	v_lshl_add_u64 v[16:17], v[20:21], 0, s[48:49]
	v_lshl_add_u64 v[22:23], v[20:21], 0, s[30:31]
	v_add_co_u32_e32 v20, vcc, s26, v20
	s_nop 0
	s_nop 0
	v_addc_co_u32_e32 v21, vcc, 0, v21, vcc
	v_cmp_lt_i32_e32 vcc, v108, v201
	v_pk_fma_f32 v[90:91], v[90:91], v[112:113], 0 op_sel_hi:[1,1,0]
	s_mov_b32 s4, 0x358637bd
	v_cndmask_b32_e32 v108, v182, v108, vcc
	v_lshlrev_b32_e32 v173, 2, v108
	s_nop 0
	s_nop 0
	s_nop 0
	s_nop 0
	s_nop 0
	s_nop 0
	s_nop 0
	s_nop 0
	s_nop 0
	s_nop 0
	v_rcp_f32_e32 v3, v3
	s_nop 0
	s_nop 0
	s_nop 0
	s_nop 0
	s_nop 0
	s_nop 0
	v_lshlrev_b32_e32 v106, 16, v119
	v_and_b32_e32 v107, 0xffff0000, v119
	v_pk_fma_f32 v[106:107], v[88:89], v[106:107], 0 op_sel_hi:[1,1,0]
	s_nop 0
	v_pk_fma_f32 v[106:107], v[92:93], v[120:121], v[106:107]
	s_nop 0
	v_pk_fma_f32 v[106:107], v[96:97], v[122:123], v[106:107]
	v_rcp_f32_e32 v2, v2
	v_pk_fma_f32 v[106:107], v[100:101], v[124:125], v[106:107]
	v_pk_fma_f32 v[90:91], v[94:95], v[114:115], v[90:91]
	v_mul_f32_e32 v108, 0xbfb8aa3b, v106
	v_mul_f32_e32 v109, 0xbfb8aa3b, v107
	v_exp_f32_e32 v108, v108
	v_exp_f32_e32 v109, v109
	v_pk_fma_f32 v[90:91], v[98:99], v[116:117], v[90:91]
	v_lshlrev_b32_e32 v94, 16, v203
	v_and_b32_e32 v95, 0xffff0000, v203
	v_pk_add_f32 v[108:109], v[108:109], 1.0 op_sel_hi:[1,0]
	v_pk_fma_f32 v[94:95], v[102:103], v[94:95], v[90:91]
	s_nop 0
	s_nop 0
	s_nop 0
	s_nop 0
	s_nop 0
	s_nop 0
	s_nop 0
	s_nop 0
	s_nop 0
	s_nop 0
	s_nop 0
	s_nop 0
	v_rcp_f32_e32 v109, v109
	s_nop 0
	s_nop 0
	s_nop 0
	s_nop 0
	s_nop 0
	s_nop 0
	v_lshlrev_b32_e32 v110, 16, v118
	v_and_b32_e32 v111, 0xffff0000, v118
	v_lshlrev_b32_e32 v126, 16, v127
	v_and_b32_e32 v127, 0xffff0000, v127
	v_pk_fma_f32 v[110:111], v[74:75], v[110:111], 0 op_sel_hi:[1,1,0]
	v_lshlrev_b32_e32 v128, 16, v129
	v_and_b32_e32 v129, 0xffff0000, v129
	v_pk_fma_f32 v[110:111], v[78:79], v[126:127], v[110:111]
	s_nop 0
	s_waitcnt vmcnt(7)
	v_pk_fma_f32 v[110:111], v[86:87], v[128:129], v[110:111]
	s_nop 0
	v_pk_fma_f32 v[110:111], v[82:83], v[130:131], v[110:111]
	v_rcp_f32_e32 v108, v108
	v_mul_f32_e32 v118, 0xbfb8aa3b, v110
	v_mul_f32_e32 v119, 0xbfb8aa3b, v111
	v_exp_f32_e32 v118, v118
	v_exp_f32_e32 v119, v119
	v_mul_f32_e32 v90, 0xbfb8aa3b, v95
	v_exp_f32_e32 v91, v90
	v_mul_f32_e32 v90, 0xbfb8aa3b, v94
	v_pk_add_f32 v[118:119], v[118:119], 1.0 op_sel_hi:[1,0]
	v_exp_f32_e32 v90, v90
	s_nop 0
	s_nop 0
	s_nop 0
	s_nop 0
	s_nop 0
	s_nop 0
	s_nop 0
	s_nop 0
	s_nop 0
	s_nop 0
	s_nop 0
	s_nop 0
	v_rcp_f32_e32 v119, v119
	s_nop 0
	s_nop 0
	s_nop 0
	s_nop 0
	s_nop 0
	v_lshlrev_b32_e32 v164, 16, v165
	v_and_b32_e32 v165, 0xffff0000, v165
	s_nop 0
	v_lshlrev_b32_e32 v132, 16, v133
	v_and_b32_e32 v133, 0xffff0000, v133
	v_pk_fma_f32 v[164:165], v[72:73], v[164:165], 0 op_sel_hi:[1,1,0]
	v_lshlrev_b32_e32 v160, 16, v161
	v_and_b32_e32 v161, 0xffff0000, v161
	v_pk_fma_f32 v[164:165], v[76:77], v[132:133], v[164:165]
	v_lshlrev_b32_e32 v162, 16, v163
	v_and_b32_e32 v163, 0xffff0000, v163
	v_pk_fma_f32 v[164:165], v[84:85], v[160:161], v[164:165]
	s_nop 0
	v_pk_fma_f32 v[164:165], v[80:81], v[162:163], v[164:165]
	s_nop 0
	v_mul_f32_e32 v204, 0xbfb8aa3b, v164
	v_mul_f32_e32 v205, 0xbfb8aa3b, v165
	v_exp_f32_e32 v204, v204
	v_exp_f32_e32 v205, v205
	v_rcp_f32_e32 v118, v118
	v_pk_fma_f32 v[88:89], v[88:89], v[120:121], 0 op_sel_hi:[1,1,0]
	v_pk_fma_f32 v[74:75], v[74:75], v[126:127], 0 op_sel_hi:[1,1,0]
	v_pk_add_f32 v[204:205], v[204:205], 1.0 op_sel_hi:[1,0]
	v_pk_fma_f32 v[88:89], v[92:93], v[122:123], v[88:89]
	s_nop 0
	s_nop 0
	v_pk_fma_f32 v[88:89], v[96:97], v[124:125], v[88:89]
	v_lshlrev_b32_e32 v92, 16, v202
	v_and_b32_e32 v93, 0xffff0000, v202
	s_nop 0
	s_nop 0
	s_nop 0
	s_nop 0
	s_nop 0
	s_nop 0
	s_nop 0
	s_nop 0
	s_nop 0
	s_nop 0
	v_rcp_f32_e32 v205, v205
	v_pk_fma_f32 v[92:93], v[100:101], v[92:93], v[88:89]
	s_nop 0
	s_nop 0
	s_nop 0
	s_nop 0
	s_nop 0
	s_nop 0
	s_nop 0
	s_nop 0
	v_pk_add_f32 v[98:99], v[90:91], 1.0 op_sel_hi:[1,0]
	v_mul_f32_e32 v88, 0xbfb8aa3b, v92
	s_nop 0
	s_nop 0
	v_mul_f32_e32 v89, 0xbfb8aa3b, v93
	v_exp_f32_e32 v88, v88
	v_exp_f32_e32 v89, v89
	s_nop 0
	s_nop 0
	s_nop 0
	s_nop 0
	s_nop 0
	s_nop 0
	s_nop 0
	s_nop 0
	s_nop 0
	s_nop 0
	v_rcp_f32_e32 v99, v99
	v_pk_fma_f32 v[74:75], v[78:79], v[128:129], v[74:75]
	s_nop 0
	s_nop 0
	s_nop 0
	s_nop 0
	s_nop 0
	s_nop 0
	s_nop 0
	s_nop 0
	v_pk_add_f32 v[96:97], v[88:89], 1.0 op_sel_hi:[1,0]
	v_rcp_f32_e32 v98, v98
	s_nop 0
	s_nop 0
	v_pk_mul_f32 v[88:89], v[94:95], v[98:99]
	v_pk_fma_f32 v[74:75], v[86:87], v[130:131], v[74:75]
	v_lshlrev_b32_e32 v78, 16, v199
	s_nop 0
	s_nop 0
	s_nop 0
	s_nop 0
	s_nop 0
	s_nop 0
	s_nop 0
	s_nop 0
	s_nop 0
	v_and_b32_e32 v79, 0xffff0000, v199
	v_pk_fma_f32 v[74:75], v[82:83], v[78:79], v[74:75]
	s_nop 0
	v_mul_f32_e32 v78, 0xbfb8aa3b, v74
	v_mul_f32_e32 v79, 0xbfb8aa3b, v75
	v_rcp_f32_e32 v97, v97
	s_nop 0
	v_exp_f32_e32 v78, v78
	v_exp_f32_e32 v79, v79
	s_nop 0
	s_nop 0
	s_nop 0
	s_nop 0
	s_nop 0
	v_pk_add_f32 v[78:79], v[78:79], 1.0 op_sel_hi:[1,0]
	s_nop 0
	s_nop 0
	s_nop 0
	s_nop 0
	v_rcp_f32_e32 v96, v96
	s_nop 0
	v_pk_mul_f32 v[82:83], v[92:93], v[96:97]
	v_pk_fma_f32 v[72:73], v[72:73], v[132:133], 0 op_sel_hi:[1,1,0]
	s_nop 0
	s_nop 0
	s_nop 0
	s_nop 0
	s_nop 0
	v_pk_fma_f32 v[72:73], v[76:77], v[160:161], v[72:73]
	s_nop 0
	s_nop 0
	v_pk_fma_f32 v[72:73], v[84:85], v[162:163], v[72:73]
	v_lshlrev_b32_e32 v76, 16, v196
	v_and_b32_e32 v77, 0xffff0000, v196
	s_nop 0
	v_pk_fma_f32 v[72:73], v[80:81], v[76:77], v[72:73]
	s_nop 0
	v_mul_f32_e32 v76, 0xbfb8aa3b, v72
	v_mul_f32_e32 v77, 0xbfb8aa3b, v73
	v_exp_f32_e32 v76, v76
	v_exp_f32_e32 v77, v77
	s_nop 0
	v_rcp_f32_e32 v79, v79
	s_nop 0
	s_nop 0
	s_nop 0
	s_nop 0
	v_pk_add_f32 v[76:77], v[76:77], 1.0 op_sel_hi:[1,0]
	s_nop 0
	s_nop 0
	s_nop 0
	s_nop 0
	s_nop 0
	s_nop 0
	v_rcp_f32_e32 v78, v78
	s_nop 0
	v_pk_mul_f32 v[80:81], v[74:75], v[78:79]
	s_nop 0
	s_nop 0
	s_nop 0
	s_nop 0
	s_nop 0
	s_nop 0
	s_nop 0
	s_nop 0
	s_nop 0
	s_nop 0
	v_rcp_f32_e32 v77, v77
	v_rcp_f32_e32 v204, v204
	s_nop 0
	s_nop 0
	s_nop 0
	s_nop 0
	s_nop 0
	s_nop 0
	s_nop 0
	s_nop 0
	v_rcp_f32_e32 v76, v76
	v_pk_mul_f32 v[90:91], v[164:165], v[204:205]
	v_pk_mul_f32 v[84:85], v[72:73], v[76:77]
	v_pk_mul_f32 v[110:111], v[110:111], v[118:119]
	v_pk_mul_f32 v[102:103], v[90:91], v[90:91]
	v_pk_mul_f32 v[72:73], v[84:85], v[84:85]
	v_pk_mul_f32 v[118:119], v[110:111], v[110:111]
	v_pk_mul_f32 v[74:75], v[80:81], v[80:81]
	v_mov_b32_e32 v76, v72
	v_mov_b32_e32 v77, v102
	v_mov_b32_e32 v102, v73
	v_pk_mul_f32 v[106:107], v[106:107], v[108:109]
	v_pk_add_f32 v[72:73], v[76:77], v[102:103]
	v_mov_b32_e32 v76, v74
	v_mov_b32_e32 v77, v118
	v_pk_mul_f32 v[108:109], v[106:107], v[106:107]
	v_pk_mul_f32 v[86:87], v[82:83], v[82:83]
	v_pk_add_f32 v[72:73], v[76:77], v[72:73]
	v_mov_b32_e32 v118, v75
	v_pk_mul_f32 v[2:3], v[104:105], v[2:3]
	v_pk_add_f32 v[72:73], v[118:119], v[72:73]
	v_mov_b32_e32 v74, v86
	v_mov_b32_e32 v75, v108
	v_pk_mul_f32 v[104:105], v[2:3], v[2:3]
	v_pk_mul_f32 v[94:95], v[88:89], v[88:89]
	v_pk_add_f32 v[72:73], v[74:75], v[72:73]
	v_mov_b32_e32 v108, v87
	v_pk_add_f32 v[72:73], v[108:109], v[72:73]
	v_mov_b32_e32 v74, v94
	v_mov_b32_e32 v75, v104
	v_pk_add_f32 v[72:73], v[74:75], v[72:73]
	v_mov_b32_e32 v104, v95
	v_pk_add_f32 v[72:73], v[104:105], v[72:73]
	ds_bpermute_b32 v75, v173, v73
	ds_bpermute_b32 v74, v173, v72
	v_xor_b32_e32 v76, 2, v182
	v_cmp_lt_i32_e32 vcc, v76, v201
	s_mov_b32 s0, 0x27ffffc
	v_and_b32_e32 v77, 48, v197
	v_cndmask_b32_e32 v76, v182, v76, vcc
	v_lshlrev_b32_e32 v118, 2, v76
	s_waitcnt lgkmcnt(0)
	v_pk_add_f32 v[72:73], v[72:73], v[74:75]
	ds_bpermute_b32 v75, v118, v73
	ds_bpermute_b32 v74, v118, v72
	v_xor_b32_e32 v76, 4, v182
	v_cmp_lt_i32_e32 vcc, v76, v201
	v_add_u32_e32 v92, 0, v197
	s_add_i32 s25, 0, 0x20500
	v_cndmask_b32_e32 v76, v182, v76, vcc
	v_lshlrev_b32_e32 v119, 2, v76
	s_waitcnt lgkmcnt(0)
	v_pk_add_f32 v[72:73], v[72:73], v[74:75]
	ds_bpermute_b32 v75, v119, v73
	ds_bpermute_b32 v74, v119, v72
	v_xor_b32_e32 v76, 8, v182
	v_cmp_lt_i32_e32 vcc, v76, v201
	global_load_dwordx4 v[28:31], v[14:15], off
	s_nop 0
	global_load_dwordx4 v[12:15], v[12:13], off offset:16
	v_cndmask_b32_e32 v76, v182, v76, vcc
	v_lshlrev_b32_e32 v120, 2, v76
	s_waitcnt lgkmcnt(0)
	v_pk_add_f32 v[72:73], v[72:73], v[74:75]
	ds_bpermute_b32 v75, v120, v73
	ds_bpermute_b32 v74, v120, v72
	v_and_or_b32 v76, v198, s0, v200
	v_lshl_or_b32 v121, v76, 6, v77
	v_mad_u64_u32 v[76:77], s[0:1], v183, s54, v[92:93]
	s_waitcnt lgkmcnt(0)
	v_pk_add_f32 v[72:73], v[72:73], v[74:75]
	global_load_dwordx4 v[32:35], v[18:19], off
	s_nop 0
	global_load_dwordx4 v[16:19], v[16:17], off offset:16
	v_pk_add_f32 v[86:87], v[72:73], s[4:5] op_sel_hi:[1,0]
	global_load_dwordx4 v[36:39], v[20:21], off
	s_nop 0
	global_load_dwordx4 v[20:23], v[22:23], off offset:16
	v_mul_f32_e32 v72, 0x4b800000, v87
	v_cmp_gt_f32_e32 vcc, s51, v87
	v_lshl_add_u32 v77, v183, 2, s25
	s_add_u32 s0, s10, s16
	v_cndmask_b32_e32 v72, v87, v72, vcc
	v_rsq_f32_e32 v72, v72
	v_mul_f32_e32 v87, 0x4b800000, v86
	s_addc_u32 s1, s11, s17
	v_lshlrev_b32_e32 v100, 16, v194
	v_mul_f32_e32 v73, 0x45800000, v72
	v_cndmask_b32_e32 v72, v72, v73, vcc
	v_mul_f32_e32 v72, 0x3db504f3, v72
	v_pk_mul_f32 v[90:91], v[90:91], v[72:73] op_sel_hi:[1,0]
	v_pk_mul_f32 v[94:95], v[110:111], v[72:73] op_sel_hi:[1,0]
	v_pk_mul_f32 v[96:97], v[106:107], v[72:73] op_sel_hi:[1,0]
	v_pk_mul_f32 v[2:3], v[2:3], v[72:73] op_sel_hi:[1,0]
	v_cvt_pk_bf16_f32 v72, v90, v91
	v_cvt_pk_bf16_f32 v73, v94, v95
	v_cvt_pk_bf16_f32 v74, v96, v97
	v_cvt_pk_bf16_f32 v75, v2, v3
	ds_write_b128 v76, v[72:75] offset:17408
	ds_read_b32 v74, v77
	v_cmp_gt_f32_e32 vcc, s51, v86
	v_and_or_b32 v72, v181, 14, v121
	v_lshlrev_b32_e32 v72, 3, v72
	v_cndmask_b32_e32 v86, v86, v87, vcc
	s_waitcnt lgkmcnt(0)
	v_mul_f32_e32 v74, 0x3fb8aa3b, v74
	v_exp_f32_e32 v98, v74
	v_rsq_f32_e32 v86, v86
	v_ashrrev_i32_e32 v73, 31, v72
	v_lshl_add_u64 v[78:79], v[72:73], 1, s[0:1]
	v_pk_mul_f32 v[72:73], v[98:99], v[90:91] op_sel_hi:[0,1]
	v_pk_mul_f32 v[74:75], v[98:99], v[94:95] op_sel_hi:[0,1]
	v_cvt_pk_bf16_f32 v72, v72, v73
	v_cvt_pk_bf16_f32 v73, v74, v75
	v_pk_mul_f32 v[74:75], v[98:99], v[96:97] op_sel_hi:[0,1]
	v_pk_mul_f32 v[2:3], v[98:99], v[2:3] op_sel_hi:[0,1]
	v_cvt_pk_bf16_f32 v74, v74, v75
	v_cvt_pk_bf16_f32 v75, v2, v3
	v_mul_f32_e32 v2, 0x45800000, v86
	v_cndmask_b32_e32 v2, v86, v2, vcc
	v_mul_f32_e32 v2, 0x3db504f3, v2
	v_pk_mul_f32 v[86:87], v[84:85], v[2:3] op_sel_hi:[1,0]
	v_pk_mul_f32 v[84:85], v[80:81], v[2:3] op_sel_hi:[1,0]
	v_pk_mul_f32 v[82:83], v[82:83], v[2:3] op_sel_hi:[1,0]
	v_pk_mul_f32 v[80:81], v[88:89], v[2:3] op_sel_hi:[1,0]
	v_lshlrev_b32_e32 v2, 16, v192
	v_and_b32_e32 v3, 0xffff0000, v192
	v_lshlrev_b32_e32 v98, 16, v193
	v_and_b32_e32 v99, 0xffff0000, v193
	v_pk_fma_f32 v[2:3], v[58:59], v[2:3], 0 op_sel_hi:[1,1,0]
	v_and_b32_e32 v101, 0xffff0000, v194
	s_waitcnt vmcnt(11)
	v_pk_fma_f32 v[2:3], v[66:67], v[98:99], v[2:3]
	v_lshlrev_b32_e32 v102, 16, v195
	v_and_b32_e32 v103, 0xffff0000, v195
	s_waitcnt vmcnt(10)
	v_pk_fma_f32 v[2:3], v[70:71], v[100:101], v[2:3]
	v_or_b32_e32 v77, 1, v181
	s_waitcnt vmcnt(8)
	v_pk_fma_f32 v[94:95], v[62:63], v[102:103], v[2:3]
	v_cvt_pk_bf16_f32 v88, v86, v87
	v_mul_f32_e32 v2, 0xbfb8aa3b, v95
	v_exp_f32_e32 v97, v2
	v_mul_f32_e32 v2, 0xbfb8aa3b, v94
	v_exp_f32_e32 v96, v2
	v_mad_u64_u32 v[2:3], s[2:3], v77, s54, v[92:93]
	v_cvt_pk_bf16_f32 v89, v84, v85
	v_pk_add_f32 v[92:93], v[96:97], 1.0 op_sel_hi:[1,0]
	v_cvt_pk_bf16_f32 v90, v82, v83
	s_nop 0
	s_nop 0
	v_cvt_pk_bf16_f32 v91, v80, v81
	ds_write_b128 v2, v[88:91] offset:17408
	s_nop 0
	s_nop 0
	s_nop 0
	s_nop 0
	s_nop 0
	s_nop 0
	s_nop 0
	s_nop 0
	s_nop 0
	s_nop 0
	v_rcp_f32_e32 v89, v93
	s_nop 0
	s_nop 0
	s_nop 0
	s_nop 0
	s_nop 0
	s_nop 0
	v_lshlrev_b32_e32 v90, 16, v188
	v_and_b32_e32 v91, 0xffff0000, v188
	v_lshlrev_b32_e32 v106, 16, v189
	v_and_b32_e32 v107, 0xffff0000, v189
	v_pk_fma_f32 v[90:91], v[56:57], v[90:91], 0 op_sel_hi:[1,1,0]
	v_lshlrev_b32_e32 v108, 16, v190
	v_and_b32_e32 v109, 0xffff0000, v190
	v_pk_fma_f32 v[90:91], v[64:65], v[106:107], v[90:91]
	v_lshlrev_b32_e32 v110, 16, v191
	v_and_b32_e32 v111, 0xffff0000, v191
	v_pk_fma_f32 v[90:91], v[68:69], v[108:109], v[90:91]
	s_nop 0
	v_pk_fma_f32 v[96:97], v[60:61], v[110:111], v[90:91]
	s_nop 0
	v_mul_f32_e32 v90, 0xbfb8aa3b, v96
	v_mul_f32_e32 v91, 0xbfb8aa3b, v97
	v_exp_f32_e32 v90, v90
	v_exp_f32_e32 v91, v91
	v_rcp_f32_e32 v88, v92
	s_nop 0
	v_pk_mul_f32 v[88:89], v[94:95], v[88:89]
	v_and_b32_e32 v113, 0xffff0000, v185
	v_pk_add_f32 v[104:105], v[90:91], 1.0 op_sel_hi:[1,0]
	v_lshlrev_b32_e32 v114, 16, v186
	s_nop 0
	s_nop 0
	s_nop 0
	s_nop 0
	s_nop 0
	s_nop 0
	s_nop 0
	s_nop 0
	s_nop 0
	s_nop 0
	s_nop 0
	s_nop 0
	v_rcp_f32_e32 v93, v105
	s_nop 0
	s_nop 0
	s_nop 0
	s_nop 0
	s_nop 0
	s_nop 0
	v_lshlrev_b32_e32 v94, 16, v184
	v_and_b32_e32 v95, 0xffff0000, v184
	v_lshlrev_b32_e32 v112, 16, v185
	v_pk_fma_f32 v[94:95], v[42:43], v[94:95], 0 op_sel_hi:[1,1,0]
	v_and_b32_e32 v115, 0xffff0000, v186
	v_pk_fma_f32 v[94:95], v[46:47], v[112:113], v[94:95]
	v_lshlrev_b32_e32 v116, 16, v187
	v_and_b32_e32 v117, 0xffff0000, v187
	v_pk_fma_f32 v[94:95], v[50:51], v[114:115], v[94:95]
	s_nop 0
	v_pk_fma_f32 v[122:123], v[54:55], v[116:117], v[94:95]
	s_nop 0
	v_mul_f32_e32 v94, 0xbfb8aa3b, v122
	v_mul_f32_e32 v95, 0xbfb8aa3b, v123
	v_exp_f32_e32 v94, v94
	v_exp_f32_e32 v95, v95
	v_rcp_f32_e32 v92, v104
	s_nop 0
	v_pk_mul_f32 v[92:93], v[96:97], v[92:93]
	v_and_b32_e32 v127, 0xffff0000, v178
	v_pk_add_f32 v[124:125], v[94:95], 1.0 op_sel_hi:[1,0]
	v_lshlrev_b32_e32 v128, 16, v179
	s_nop 0
	s_nop 0
	s_nop 0
	s_nop 0
	s_nop 0
	s_nop 0
	s_nop 0
	s_nop 0
	s_nop 0
	s_nop 0
	s_nop 0
	s_nop 0
	v_rcp_f32_e32 v97, v125
	s_nop 0
	s_nop 0
	s_nop 0
	s_nop 0
	s_nop 0
	s_nop 0
	v_lshlrev_b32_e32 v104, 16, v177
	v_and_b32_e32 v105, 0xffff0000, v177
	v_lshlrev_b32_e32 v126, 16, v178
	v_pk_fma_f32 v[104:105], v[40:41], v[104:105], 0 op_sel_hi:[1,1,0]
	v_and_b32_e32 v129, 0xffff0000, v179
	v_pk_fma_f32 v[104:105], v[44:45], v[126:127], v[104:105]
	v_lshlrev_b32_e32 v130, 16, v180
	v_and_b32_e32 v131, 0xffff0000, v180
	v_pk_fma_f32 v[104:105], v[48:49], v[128:129], v[104:105]
	s_nop 0
	v_pk_fma_f32 v[132:133], v[52:53], v[130:131], v[104:105]
	s_nop 0
	v_mul_f32_e32 v104, 0xbfb8aa3b, v132
	v_mul_f32_e32 v105, 0xbfb8aa3b, v133
	v_exp_f32_e32 v104, v104
	v_exp_f32_e32 v105, v105
	v_rcp_f32_e32 v96, v124
	s_nop 0
	v_pk_mul_f32 v[96:97], v[122:123], v[96:97]
	v_pk_fma_f32 v[58:59], v[58:59], v[98:99], 0 op_sel_hi:[1,1,0]
	v_pk_add_f32 v[160:161], v[104:105], 1.0 op_sel_hi:[1,0]
	v_pk_fma_f32 v[58:59], v[66:67], v[100:101], v[58:59]
	s_nop 0
	s_nop 0
	v_pk_fma_f32 v[58:59], v[70:71], v[102:103], v[58:59]
	v_lshlrev_b32_e32 v66, 16, v176
	v_and_b32_e32 v67, 0xffff0000, v176
	s_nop 0
	s_nop 0
	s_nop 0
	s_nop 0
	s_nop 0
	s_nop 0
	s_nop 0
	s_nop 0
	s_nop 0
	s_nop 0
	v_pk_fma_f32 v[62:63], v[62:63], v[66:67], v[58:59]
	v_rcp_f32_e32 v123, v161
	s_nop 0
	v_mul_f32_e32 v58, 0xbfb8aa3b, v63
	s_nop 0
	s_nop 0
	v_exp_f32_e32 v59, v58
	v_mul_f32_e32 v58, 0xbfb8aa3b, v62
	s_nop 0
	v_exp_f32_e32 v58, v58
	s_nop 0
	s_nop 0
	s_nop 0
	s_nop 0
	v_pk_add_f32 v[66:67], v[58:59], 1.0 op_sel_hi:[1,0]
	v_pk_fma_f32 v[56:57], v[56:57], v[106:107], 0 op_sel_hi:[1,1,0]
	s_nop 0
	s_nop 0
	v_pk_fma_f32 v[56:57], v[64:65], v[108:109], v[56:57]
	v_lshlrev_b32_e32 v64, 16, v175
	v_pk_fma_f32 v[56:57], v[68:69], v[110:111], v[56:57]
	s_nop 0
	s_nop 0
	s_nop 0
	s_nop 0
	s_nop 0
	s_nop 0
	s_nop 0
	s_nop 0
	s_nop 0
	s_nop 0
	v_and_b32_e32 v65, 0xffff0000, v175
	v_rcp_f32_e32 v67, v67
	s_nop 0
	v_pk_fma_f32 v[60:61], v[60:61], v[64:65], v[56:57]
	s_nop 0
	s_nop 0
	v_mul_f32_e32 v56, 0xbfb8aa3b, v60
	v_mul_f32_e32 v57, 0xbfb8aa3b, v61
	s_nop 0
	v_exp_f32_e32 v56, v56
	v_exp_f32_e32 v57, v57
	s_nop 0
	s_nop 0
	s_nop 0
	s_nop 0
	v_pk_add_f32 v[64:65], v[56:57], 1.0 op_sel_hi:[1,0]
	v_rcp_f32_e32 v66, v66
	s_nop 0
	s_nop 0
	v_pk_mul_f32 v[56:57], v[62:63], v[66:67]
	v_pk_fma_f32 v[42:43], v[42:43], v[112:113], 0 op_sel_hi:[1,1,0]
	v_pk_fma_f32 v[40:41], v[40:41], v[126:127], 0 op_sel_hi:[1,1,0]
	s_nop 0
	s_nop 0
	s_nop 0
	s_nop 0
	s_nop 0
	s_nop 0
	s_nop 0
	s_nop 0
	s_nop 0
	v_pk_fma_f32 v[42:43], v[46:47], v[114:115], v[42:43]
	v_lshlrev_b32_e32 v46, 16, v174
	v_pk_fma_f32 v[42:43], v[50:51], v[116:117], v[42:43]
	v_and_b32_e32 v47, 0xffff0000, v174
	v_pk_fma_f32 v[42:43], v[54:55], v[46:47], v[42:43]
	s_nop 0
	v_mul_f32_e32 v46, 0xbfb8aa3b, v42
	v_mul_f32_e32 v47, 0xbfb8aa3b, v43
	v_rcp_f32_e32 v65, v65
	s_nop 0
	v_exp_f32_e32 v46, v46
	v_exp_f32_e32 v47, v47
	s_nop 0
	s_nop 0
	s_nop 0
	s_nop 0
	s_nop 0
	v_pk_add_f32 v[46:47], v[46:47], 1.0 op_sel_hi:[1,0]
	s_nop 0
	s_nop 0
	s_nop 0
	s_nop 0
	v_rcp_f32_e32 v64, v64
	s_nop 0
	v_pk_mul_f32 v[50:51], v[60:61], v[64:65]
	v_pk_fma_f32 v[40:41], v[44:45], v[128:129], v[40:41]
	s_nop 0
	s_nop 0
	s_nop 0
	s_nop 0
	s_nop 0
	v_pk_fma_f32 v[40:41], v[48:49], v[130:131], v[40:41]
	v_lshlrev_b32_e32 v44, 16, v172
	v_and_b32_e32 v45, 0xffff0000, v172
	s_nop 0
	s_nop 0
	v_pk_fma_f32 v[40:41], v[52:53], v[44:45], v[40:41]
	s_nop 0
	v_mul_f32_e32 v44, 0xbfb8aa3b, v40
	v_mul_f32_e32 v45, 0xbfb8aa3b, v41
	v_exp_f32_e32 v44, v44
	v_exp_f32_e32 v45, v45
	s_nop 0
	s_nop 0
	v_rcp_f32_e32 v47, v47
	s_nop 0
	s_nop 0
	s_nop 0
	v_pk_add_f32 v[44:45], v[44:45], 1.0 op_sel_hi:[1,0]
	s_nop 0
	s_nop 0
	s_nop 0
	s_nop 0
	s_nop 0
	s_nop 0
	s_nop 0
	v_rcp_f32_e32 v46, v46
	s_nop 0
	s_nop 0
	s_nop 0
	s_nop 0
	s_nop 0
	s_nop 0
	s_nop 0
	s_nop 0
	s_nop 0
	s_nop 0
	v_rcp_f32_e32 v45, v45
	v_rcp_f32_e32 v122, v160
	s_nop 0
	s_nop 0
	s_nop 0
	s_nop 0
	s_nop 0
	s_nop 0
	s_nop 0
	s_nop 0
	v_rcp_f32_e32 v44, v44
	v_pk_mul_f32 v[58:59], v[132:133], v[122:123]
	v_pk_mul_f32 v[44:45], v[40:41], v[44:45]
	v_pk_mul_f32 v[70:71], v[58:59], v[58:59]
	v_pk_mul_f32 v[46:47], v[42:43], v[46:47]
	v_pk_mul_f32 v[40:41], v[44:45], v[44:45]
	v_pk_mul_f32 v[104:105], v[96:97], v[96:97]
	v_pk_mul_f32 v[42:43], v[46:47], v[46:47]
	v_mov_b32_e32 v48, v40
	v_mov_b32_e32 v49, v70
	v_mov_b32_e32 v70, v41
	v_pk_add_f32 v[40:41], v[48:49], v[70:71]
	v_mov_b32_e32 v48, v42
	v_mov_b32_e32 v49, v104
	v_pk_mul_f32 v[94:95], v[92:93], v[92:93]
	v_pk_mul_f32 v[54:55], v[50:51], v[50:51]
	v_pk_add_f32 v[40:41], v[48:49], v[40:41]
	v_mov_b32_e32 v104, v43
	v_pk_add_f32 v[40:41], v[104:105], v[40:41]
	v_mov_b32_e32 v42, v54
	v_mov_b32_e32 v43, v94
	v_pk_mul_f32 v[90:91], v[88:89], v[88:89]
	v_pk_mul_f32 v[62:63], v[56:57], v[56:57]
	v_pk_add_f32 v[40:41], v[42:43], v[40:41]
	v_mov_b32_e32 v94, v55
	v_pk_add_f32 v[40:41], v[94:95], v[40:41]
	v_mov_b32_e32 v42, v62
	v_mov_b32_e32 v43, v90
	v_pk_add_f32 v[40:41], v[42:43], v[40:41]
	v_mov_b32_e32 v90, v63
	v_pk_add_f32 v[40:41], v[90:91], v[40:41]
	v_lshl_add_u32 v3, v77, 2, s25
	ds_bpermute_b32 v43, v173, v41
	ds_bpermute_b32 v42, v173, v40
	ds_read_b32 v3, v3
	s_mov_b32 s2, 0x13800000
	v_add_co_u32_e32 v48, vcc, s2, v78
	s_waitcnt lgkmcnt(1)
	v_pk_add_f32 v[42:43], v[40:41], v[42:43]
	v_addc_co_u32_e32 v49, vcc, 0, v79, vcc
	s_waitcnt lgkmcnt(0)
	v_mul_f32_e32 v3, 0x3fb8aa3b, v3
	ds_bpermute_b32 v53, v118, v43
	ds_bpermute_b32 v52, v118, v42
	global_store_dwordx4 v[48:49], v[72:75], off
	v_exp_f32_e32 v48, v3
	v_and_or_b32 v3, v77, 15, v121
	v_lshlrev_b32_e32 v66, 16, v144
	s_waitcnt lgkmcnt(0)
	v_pk_add_f32 v[52:53], v[42:43], v[52:53]
	v_pk_mul_f32 v[40:41], v[48:49], v[86:87] op_sel_hi:[0,1]
	v_pk_mul_f32 v[54:55], v[48:49], v[84:85] op_sel_hi:[0,1]
	v_cvt_pk_bf16_f32 v40, v40, v41
	v_cvt_pk_bf16_f32 v41, v54, v55
	ds_bpermute_b32 v55, v119, v53
	ds_bpermute_b32 v54, v119, v52
	v_pk_mul_f32 v[42:43], v[48:49], v[82:83] op_sel_hi:[0,1]
	v_pk_mul_f32 v[48:49], v[48:49], v[80:81] op_sel_hi:[0,1]
	v_cvt_pk_bf16_f32 v42, v42, v43
	v_cvt_pk_bf16_f32 v43, v48, v49
	s_waitcnt lgkmcnt(0)
	v_pk_add_f32 v[48:49], v[52:53], v[54:55]
	ds_bpermute_b32 v53, v120, v49
	ds_bpermute_b32 v52, v120, v48
	v_lshlrev_b32_e32 v54, 3, v3
	v_ashrrev_i32_e32 v55, 31, v54
	v_lshl_add_u64 v[54:55], v[54:55], 1, s[0:1]
	v_and_b32_e32 v67, 0xffff0000, v144
	s_waitcnt lgkmcnt(0)
	v_pk_add_f32 v[48:49], v[48:49], v[52:53]
	v_add_co_u32_e64 v52, s[0:1], s2, v54
	v_pk_add_f32 v[48:49], v[48:49], s[4:5] op_sel_hi:[1,0]
	s_nop 0
	v_addc_co_u32_e64 v53, s[0:1], 0, v55, s[0:1]
	v_mul_f32_e32 v3, 0x4b800000, v49
	v_cmp_gt_f32_e32 vcc, s51, v49
	global_store_dwordx4 v[52:53], v[40:43], off
	s_waitcnt vmcnt(9)
	v_pk_fma_f32 v[66:67], v[8:9], v[66:67], 0 op_sel_hi:[1,1,0]
	v_cndmask_b32_e32 v3, v49, v3, vcc
	v_rsq_f32_e32 v3, v3
	v_and_b32_e32 v73, 0xffff0000, v140
	s_bfe_u32 s28, s24, 0x20006
	s_ashr_i32 s26, s24, 7
	v_mul_f32_e32 v40, 0x45800000, v3
	v_cndmask_b32_e32 v40, v3, v40, vcc
	v_mul_f32_e32 v3, 0x4b800000, v48
	v_cmp_gt_f32_e32 vcc, s51, v48
	v_pk_mul_f32 v[42:43], v[58:59], v[40:41] op_sel_hi:[1,0]
	v_pk_mul_f32 v[52:53], v[96:97], v[40:41] op_sel_hi:[1,0]
	v_cndmask_b32_e32 v3, v48, v3, vcc
	v_rsq_f32_e32 v3, v3
	v_pk_mul_f32 v[54:55], v[92:93], v[40:41] op_sel_hi:[1,0]
	v_pk_mul_f32 v[58:59], v[88:89], v[40:41] op_sel_hi:[1,0]
	v_cvt_pk_bf16_f32 v40, v42, v43
	v_cvt_pk_bf16_f32 v41, v52, v53
	v_cvt_pk_bf16_f32 v42, v54, v55
	v_cvt_pk_bf16_f32 v43, v58, v59
	ds_write_b128 v76, v[40:43]
	v_mul_f32_e32 v40, 0x45800000, v3
	v_cndmask_b32_e32 v48, v3, v40, vcc
	v_pk_mul_f32 v[54:55], v[46:47], v[48:49] op_sel_hi:[1,0]
	v_lshlrev_b32_e32 v46, 16, v168
	v_and_b32_e32 v47, 0xffff0000, v168
	v_lshlrev_b32_e32 v40, 16, v169
	v_and_b32_e32 v41, 0xffff0000, v169
	s_waitcnt vmcnt(8)
	v_pk_fma_f32 v[46:47], v[24:25], v[46:47], 0 op_sel_hi:[1,1,0]
	v_lshlrev_b32_e32 v42, 16, v170
	v_and_b32_e32 v43, 0xffff0000, v170
	s_waitcnt vmcnt(7)
	v_pk_fma_f32 v[46:47], v[28:29], v[40:41], v[46:47]
	v_pk_mul_f32 v[52:53], v[44:45], v[48:49] op_sel_hi:[1,0]
	v_lshlrev_b32_e32 v44, 16, v171
	v_and_b32_e32 v45, 0xffff0000, v171
	s_waitcnt vmcnt(5)
	v_pk_fma_f32 v[46:47], v[32:33], v[42:43], v[46:47]
	v_pk_mul_f32 v[50:51], v[50:51], v[48:49] op_sel_hi:[1,0]
	s_waitcnt vmcnt(3)
	v_pk_fma_f32 v[58:59], v[36:37], v[44:45], v[46:47]
	v_cvt_pk_bf16_f32 v46, v52, v53
	v_mul_f32_e32 v3, 0xbfb8aa3b, v58
	v_exp_f32_e32 v60, v3
	v_mul_f32_e32 v3, 0xbfb8aa3b, v59
	v_exp_f32_e32 v61, v3
	v_cvt_pk_bf16_f32 v47, v54, v55
	v_pk_mul_f32 v[56:57], v[56:57], v[48:49] op_sel_hi:[1,0]
	v_cvt_pk_bf16_f32 v48, v50, v51
	v_pk_add_f32 v[52:53], v[60:61], 1.0 op_sel_hi:[1,0]
	v_cvt_pk_bf16_f32 v49, v56, v57
	s_nop 0
	s_nop 0
	ds_write_b128 v2, v[46:49]
	v_and_b32_e32 v55, 0xffff0000, v148
	s_nop 0
	s_nop 0
	s_nop 0
	s_nop 0
	s_nop 0
	s_nop 0
	s_nop 0
	s_nop 0
	s_nop 0
	v_lshlrev_b32_e32 v54, 16, v148
	v_lshlrev_b32_e32 v46, 16, v149
	v_and_b32_e32 v47, 0xffff0000, v149
	v_pk_fma_f32 v[54:55], v[26:27], v[54:55], 0 op_sel_hi:[1,1,0]
	s_nop 0
	v_lshlrev_b32_e32 v48, 16, v150
	v_and_b32_e32 v49, 0xffff0000, v150
	v_pk_fma_f32 v[54:55], v[30:31], v[46:47], v[54:55]
	v_lshlrev_b32_e32 v50, 16, v151
	v_and_b32_e32 v51, 0xffff0000, v151
	v_pk_fma_f32 v[54:55], v[34:35], v[48:49], v[54:55]
	v_rcp_f32_e32 v53, v53
	v_pk_fma_f32 v[60:61], v[38:39], v[50:51], v[54:55]
	s_nop 0
	v_mul_f32_e32 v54, 0xbfb8aa3b, v60
	v_mul_f32_e32 v55, 0xbfb8aa3b, v61
	v_exp_f32_e32 v54, v54
	v_exp_f32_e32 v55, v55
	s_nop 0
	s_nop 0
	s_nop 0
	s_nop 0
	s_nop 0
	v_pk_add_f32 v[62:63], v[54:55], 1.0 op_sel_hi:[1,0]
	s_nop 0
	s_nop 0
	s_nop 0
	s_nop 0
	v_rcp_f32_e32 v52, v52
	s_nop 0
	v_pk_mul_f32 v[64:65], v[58:59], v[52:53]
	s_nop 0
	s_nop 0
	s_nop 0
	s_nop 0
	s_nop 0
	s_nop 0
	s_nop 0
	s_nop 0
	v_lshlrev_b32_e32 v52, 16, v145
	v_and_b32_e32 v53, 0xffff0000, v145
	s_nop 0
	v_lshlrev_b32_e32 v54, 16, v146
	v_and_b32_e32 v55, 0xffff0000, v146
	v_pk_fma_f32 v[66:67], v[12:13], v[52:53], v[66:67]
	s_nop 0
	v_lshlrev_b32_e32 v56, 16, v147
	v_and_b32_e32 v57, 0xffff0000, v147
	v_pk_fma_f32 v[66:67], v[16:17], v[54:55], v[66:67]
	v_rcp_f32_e32 v59, v63
	s_waitcnt vmcnt(2)
	v_pk_fma_f32 v[66:67], v[20:21], v[56:57], v[66:67]
	s_nop 0
	v_mul_f32_e32 v68, 0xbfb8aa3b, v66
	v_mul_f32_e32 v69, 0xbfb8aa3b, v67
	v_exp_f32_e32 v68, v68
	v_exp_f32_e32 v69, v69
	s_nop 0
	s_nop 0
	s_nop 0
	s_nop 0
	v_pk_add_f32 v[68:69], v[68:69], 1.0 op_sel_hi:[1,0]
	s_nop 0
	s_nop 0
	s_nop 0
	s_nop 0
	s_nop 0
	v_rcp_f32_e32 v58, v62
	s_nop 0
	s_nop 0
	s_nop 0
	v_pk_mul_f32 v[62:63], v[60:61], v[58:59]
	s_nop 0
	s_nop 0
	s_nop 0
	s_nop 0
	s_nop 0
	v_lshlrev_b32_e32 v72, 16, v140
	v_lshlrev_b32_e32 v58, 16, v141
	v_and_b32_e32 v59, 0xffff0000, v141
	v_pk_fma_f32 v[72:73], v[10:11], v[72:73], 0 op_sel_hi:[1,1,0]
	s_nop 0
	v_lshlrev_b32_e32 v60, 16, v142
	v_and_b32_e32 v61, 0xffff0000, v142
	v_pk_fma_f32 v[72:73], v[14:15], v[58:59], v[72:73]
	s_nop 0
	v_lshlrev_b32_e32 v70, 16, v143
	v_and_b32_e32 v71, 0xffff0000, v143
	v_pk_fma_f32 v[72:73], v[18:19], v[60:61], v[72:73]
	v_rcp_f32_e32 v69, v69
	v_pk_fma_f32 v[72:73], v[22:23], v[70:71], v[72:73]
	s_nop 0
	v_mul_f32_e32 v74, 0xbfb8aa3b, v73
	v_exp_f32_e32 v75, v74
	v_mul_f32_e32 v74, 0xbfb8aa3b, v72
	v_exp_f32_e32 v74, v74
	s_nop 0
	s_nop 0
	s_nop 0
	s_nop 0
	s_nop 0
	v_pk_add_f32 v[74:75], v[74:75], 1.0 op_sel_hi:[1,0]
	s_nop 0
	s_nop 0
	s_nop 0
	s_nop 0
	v_rcp_f32_e32 v68, v68
	s_nop 0
	v_pk_mul_f32 v[66:67], v[66:67], v[68:69]
	s_nop 0
	s_nop 0
	s_nop 0
	s_nop 0
	s_nop 0
	s_nop 0
	s_nop 0
	s_nop 0
	s_nop 0
	s_nop 0
	v_rcp_f32_e32 v69, v75
	v_pk_fma_f32 v[24:25], v[24:25], v[40:41], 0 op_sel_hi:[1,1,0]
	s_nop 0
	s_nop 0
	s_nop 0
	s_nop 0
	s_nop 0
	s_nop 0
	v_pk_fma_f32 v[24:25], v[28:29], v[42:43], v[24:25]
	s_nop 0
	v_pk_fma_f32 v[24:25], v[32:33], v[44:45], v[24:25]
	v_lshlrev_b32_e32 v28, 16, v139
	v_and_b32_e32 v29, 0xffff0000, v139
	s_nop 0
	v_pk_fma_f32 v[24:25], v[36:37], v[28:29], v[24:25]
	v_rcp_f32_e32 v68, v74
	v_mul_f32_e32 v3, 0xbfb8aa3b, v24
	v_exp_f32_e32 v28, v3
	v_mul_f32_e32 v3, 0xbfb8aa3b, v25
	v_exp_f32_e32 v29, v3
	v_pk_mul_f32 v[32:33], v[72:73], v[68:69]
	v_pk_fma_f32 v[26:27], v[26:27], v[46:47], 0 op_sel_hi:[1,1,0]
	v_cvt_pk_bf16_f32 v43, v32, v33
	v_pk_add_f32 v[28:29], v[28:29], 1.0 op_sel_hi:[1,0]
	v_pk_fma_f32 v[26:27], v[30:31], v[48:49], v[26:27]
	s_nop 0
	s_nop 0
	v_pk_fma_f32 v[26:27], v[34:35], v[50:51], v[26:27]
	v_lshlrev_b32_e32 v30, 16, v138
	v_and_b32_e32 v31, 0xffff0000, v138
	s_nop 0
	s_nop 0
	s_nop 0
	s_nop 0
	s_nop 0
	s_nop 0
	s_nop 0
	s_nop 0
	s_nop 0
	v_pk_fma_f32 v[26:27], v[38:39], v[30:31], v[26:27]
	s_nop 0
	v_mul_f32_e32 v30, 0xbfb8aa3b, v26
	v_mul_f32_e32 v31, 0xbfb8aa3b, v27
	v_rcp_f32_e32 v29, v29
	s_nop 0
	v_exp_f32_e32 v30, v30
	v_exp_f32_e32 v31, v31
	s_nop 0
	s_nop 0
	s_nop 0
	s_nop 0
	s_nop 0
	v_pk_add_f32 v[30:31], v[30:31], 1.0 op_sel_hi:[1,0]
	s_nop 0
	s_nop 0
	s_nop 0
	s_nop 0
	v_rcp_f32_e32 v28, v28
	s_nop 0
	v_pk_mul_f32 v[24:25], v[24:25], v[28:29]
	s_nop 0
	s_nop 0
	s_nop 0
	s_nop 0
	v_pk_fma_f32 v[8:9], v[8:9], v[52:53], 0 op_sel_hi:[1,1,0]
	s_nop 0
	v_pk_fma_f32 v[8:9], v[12:13], v[54:55], v[8:9]
	s_nop 0
	v_pk_fma_f32 v[8:9], v[16:17], v[56:57], v[8:9]
	v_lshlrev_b32_e32 v12, 16, v137
	v_and_b32_e32 v13, 0xffff0000, v137
	s_nop 0
	s_nop 0
	v_pk_fma_f32 v[8:9], v[20:21], v[12:13], v[8:9]
	s_nop 0
	v_mul_f32_e32 v12, 0xbfb8aa3b, v8
	v_mul_f32_e32 v13, 0xbfb8aa3b, v9
	v_exp_f32_e32 v12, v12
	v_exp_f32_e32 v13, v13
	s_nop 0
	v_rcp_f32_e32 v29, v31
	s_nop 0
	s_nop 0
	s_nop 0
	v_pk_add_f32 v[12:13], v[12:13], 1.0 op_sel_hi:[1,0]
	s_nop 0
	s_nop 0
	s_nop 0
	s_nop 0
	s_nop 0
	s_nop 0
	s_nop 0
	v_rcp_f32_e32 v28, v30
	s_nop 0
	s_nop 0
	s_nop 0
	v_pk_mul_f32 v[16:17], v[26:27], v[28:29]
	s_nop 0
	s_nop 0
	v_pk_fma_f32 v[10:11], v[10:11], v[58:59], 0 op_sel_hi:[1,1,0]
	s_nop 0
	v_pk_fma_f32 v[10:11], v[14:15], v[60:61], v[10:11]
	s_nop 0
	s_nop 0
	v_pk_fma_f32 v[10:11], v[18:19], v[70:71], v[10:11]
	v_lshlrev_b32_e32 v14, 16, v136
	v_and_b32_e32 v15, 0xffff0000, v136
	s_nop 0
	v_pk_fma_f32 v[10:11], v[22:23], v[14:15], v[10:11]
	s_nop 0
	v_mul_f32_e32 v14, 0xbfb8aa3b, v11
	v_exp_f32_e32 v15, v14
	v_mul_f32_e32 v14, 0xbfb8aa3b, v10
	v_exp_f32_e32 v14, v14
	v_rcp_f32_e32 v13, v13
	s_nop 0
	s_nop 0
	s_nop 0
	s_nop 0
	s_nop 0
	v_pk_add_f32 v[14:15], v[14:15], 1.0 op_sel_hi:[1,0]
	s_nop 0
	s_nop 0
	s_nop 0
	s_nop 0
	s_nop 0
	v_rcp_f32_e32 v12, v12
	s_nop 0
	s_nop 0
	s_nop 0
	v_pk_mul_f32 v[12:13], v[8:9], v[12:13]
	s_nop 0
	s_nop 0
	s_nop 0
	s_nop 0
	s_nop 0
	s_nop 0
	s_nop 0
	v_rcp_f32_e32 v9, v15
	s_lshl_b32 s29, s28, 4
	s_nop 0
	s_nop 0
	s_nop 0
	s_nop 0
	s_nop 0
	s_nop 0
	s_nop 0
	s_nop 0
	v_rcp_f32_e32 v8, v14
	s_nop 0
	v_pk_mul_f32 v[14:15], v[10:11], v[8:9]
	v_cvt_pk_bf16_f32 v8, v24, v25
	v_cvt_pk_bf16_f32 v9, v16, v17
	v_cvt_pk_bf16_f32 v10, v12, v13
	v_cvt_pk_bf16_f32 v11, v14, v15
	v_and_b32_e32 v3, 48, v134
	ds_write_b128 v2, v[8:11] offset:34816
	s_and_b32 s27, s26, -2
	v_or_b32_e32 v2, s29, v1
	v_add_u32_e32 v48, 0, v3
	v_cvt_pk_bf16_f32 v40, v64, v65
	v_cvt_pk_bf16_f32 v41, v62, v63
	v_cvt_pk_bf16_f32 v42, v66, v67
	v_mad_u32_u24 v55, v2, s54, v48
	v_lshl_or_b32 v59, s27, 4, v1
	ds_write_b128 v76, v[40:43] offset:34816
	s_waitcnt lgkmcnt(0)
	s_barrier
	s_lshr_b32 s0, s24, 6
	s_and_b32 s1, s0, 3
	s_lshr_b32 s2, s0, 2
	s_lshl_b32 s2, s2, 1
	v_lshrrev_b32_e32 v3, 4, v134
	v_mul_u32_u24_e32 v4, 0x110, v1
	v_lshl_add_u32 v4, v3, 4, v4
	s_mul_i32 s3, s1, 0x1100
	s_mul_i32 s4, s2, 0x1100
	v_add_u32_e32 v2, s3, v4
	v_add_u32_e32 v4, s4, v4
	s_lshl_b32 s5, s1, 6
	s_add_u32 s5, s5, 0x20500
	v_lshl_add_u32 v5, v3, 4, s5
	s_lshl_b32 s6, s2, 6
	s_add_u32 s6, s6, 0x20500
	v_lshl_add_u32 v6, v1, 2, s6
	v_mul_u32_u24_e32 v7, 0x110, v1
	v_lshl_add_u32 v7, v3, 4, v7
	s_lshl_b32 s7, s1, 6
	s_add_u32 s7, s7, s4
	s_add_u32 s7, s7, 0xcc00
	v_add_u32_e32 v7, s7, v7
	v_mul_u32_u24_e32 v9, 0x240, v3
	v_lshl_add_u32 v9, v1, 1, v9
	s_mul_i32 s26, s1, 0x900
	s_lshl_b32 s27, s2, 5
	s_add_u32 s26, s26, s27
	s_add_u32 s26, s26, 0x11000
	v_add_u32_e32 v9, s26, v9
	v_lshrrev_b32_e32 v10, 1, v3
	v_lshlrev_b32_e32 v10, 8, v10
	v_lshl_add_u32 v10, v1, 4, v10
	v_and_b32_e32 v11, 1, v3
	v_lshl_add_u32 v10, v11, 3, v10
	s_lshl_b32 s27, s2, 11
	s_lshl_b32 s28, s1, 9
	s_add_u32 s27, s27, s28
	v_add_u32_e32 v10, s27, v10
	s_add_u32 s26, s10, s18
	s_addc_u32 s27, s11, s19
	s_lshl_b32 s28, s2, 4
	s_lshl_b32 s29, s1, 4
	s_sub_i32 s28, s28, s29
	v_lshlrev_b32_e32 v11, 2, v3
	v_sub_u32_e32 v11, v1, v11
	v_add_u32_e32 v11, s28, v11
	v_add_u32_e32 v70, 16, v11
	ds_read_b128 v[60:63], v5
	ds_read_b128 v[64:67], v5 offset:256
	ds_read_b32 v68, v6
	ds_read_b32 v69, v6 offset:64
	ds_read_b128 v[12:15], v2 offset:0
	ds_read_b128 v[28:31], v4 offset:0
	ds_read_b128 v[44:47], v4 offset:17408
	ds_read_b128 v[16:19], v2 offset:64
	ds_read_b128 v[32:35], v4 offset:64
	ds_read_b128 v[48:51], v4 offset:17472
	ds_read_b128 v[20:23], v2 offset:128
	ds_read_b128 v[36:39], v4 offset:128
	ds_read_b128 v[52:55], v4 offset:17536
	ds_read_b128 v[24:27], v2 offset:192
	ds_read_b128 v[40:43], v4 offset:192
	ds_read_b128 v[56:59], v4 offset:17600
	ds_read_b128 v[136:139], v4 offset:4352
	ds_read_b128 v[168:171], v4 offset:21760
	ds_read_b128 v[140:143], v4 offset:4416
	ds_read_b128 v[172:175], v4 offset:21824
	ds_read_b128 v[144:147], v4 offset:4480
	ds_read_b128 v[176:179], v4 offset:21888
	ds_read_b128 v[148:151], v4 offset:4544
	ds_read_b128 v[184:187], v4 offset:21952
	s_waitcnt lgkmcnt(14)
	v_mfma_f32_16x16x32_bf16 v[160:163], v[12:15], v[28:31], 0
	v_mfma_f32_16x16x32_bf16 v[200:203], v[12:15], v[44:47], 0
	s_waitcnt lgkmcnt(14)
	v_mfma_f32_16x16x32_bf16 v[160:163], v[16:19], v[32:35], v[160:163]
	v_mfma_f32_16x16x32_bf16 v[200:203], v[16:19], v[48:51], v[200:203]
	s_waitcnt lgkmcnt(11)
	v_mfma_f32_16x16x32_bf16 v[160:163], v[20:23], v[36:39], v[160:163]
	v_mfma_f32_16x16x32_bf16 v[200:203], v[20:23], v[52:55], v[200:203]
	s_waitcnt lgkmcnt(8)
	v_mfma_f32_16x16x32_bf16 v[160:163], v[24:27], v[40:43], v[160:163]
	v_mfma_f32_16x16x32_bf16 v[200:203], v[24:27], v[56:59], v[200:203]
	s_waitcnt lgkmcnt(6)
	v_mfma_f32_16x16x32_bf16 v[234:237], v[12:15], v[136:139], 0
	v_mfma_f32_16x16x32_bf16 v[238:241], v[12:15], v[168:171], 0
	s_waitcnt lgkmcnt(4)
	v_mfma_f32_16x16x32_bf16 v[234:237], v[16:19], v[140:143], v[234:237]
	v_mfma_f32_16x16x32_bf16 v[238:241], v[16:19], v[172:175], v[238:241]
	s_waitcnt lgkmcnt(2)
	v_mfma_f32_16x16x32_bf16 v[234:237], v[20:23], v[144:147], v[234:237]
	v_mfma_f32_16x16x32_bf16 v[238:241], v[20:23], v[176:179], v[238:241]
	s_waitcnt lgkmcnt(0)
	v_mfma_f32_16x16x32_bf16 v[234:237], v[24:27], v[148:151], v[234:237]
	v_mfma_f32_16x16x32_bf16 v[238:241], v[24:27], v[184:187], v[238:241]
	v_cmp_lt_i32_e64 s[0:1], v11, 0
	v_cmp_lt_i32_e64 s[2:3], v11, 1
	v_cmp_lt_i32_e64 s[4:5], v11, 2
	v_cmp_lt_i32_e64 s[6:7], v11, 3
	v_cmp_lt_i32_e64 s[28:29], v70, 0
	v_cmp_lt_i32_e64 s[30:31], v70, 1
	v_cmp_lt_i32_e64 s[32:33], v70, 2
	v_cmp_lt_i32_e64 s[34:35], v70, 3
	v_sub_f32_e32 v70, v60, v68
	v_sub_f32_e32 v164, v68, v60
	v_sub_f32_e32 v71, v61, v68
	v_sub_f32_e32 v165, v68, v61
	v_sub_f32_e32 v72, v62, v68
	v_sub_f32_e32 v180, v68, v62
	v_sub_f32_e32 v73, v63, v68
	v_sub_f32_e32 v181, v68, v63
	v_mul_f32_e32 v70, 0x3fb8aa3b, v70
	v_mul_f32_e32 v164, 0x3fb8aa3b, v164
	v_mul_f32_e32 v71, 0x3fb8aa3b, v71
	v_mul_f32_e32 v165, 0x3fb8aa3b, v165
	v_mul_f32_e32 v72, 0x3fb8aa3b, v72
	v_mul_f32_e32 v180, 0x3fb8aa3b, v180
	v_mul_f32_e32 v73, 0x3fb8aa3b, v73
	v_mul_f32_e32 v181, 0x3fb8aa3b, v181
	v_exp_f32_e32 v70, v70
	v_exp_f32_e32 v164, v164
	v_exp_f32_e32 v71, v71
	v_exp_f32_e32 v165, v165
	v_exp_f32_e32 v72, v72
	v_exp_f32_e32 v180, v180
	v_exp_f32_e32 v73, v73
	v_exp_f32_e32 v181, v181
	v_mul_f32_e32 v160, v160, v70
	v_mul_f32_e32 v200, v200, v164
	v_mul_f32_e32 v161, v161, v71
	v_mul_f32_e32 v201, v201, v165
	v_mul_f32_e32 v162, v162, v72
	v_mul_f32_e32 v202, v202, v180
	v_mul_f32_e32 v163, v163, v73
	v_mul_f32_e32 v203, v203, v181
	v_mul_f32_e32 v160, v64, v160
	v_mul_f32_e32 v161, v65, v161
	v_mul_f32_e32 v162, v66, v162
	v_mul_f32_e32 v163, v67, v163
	v_cndmask_b32_e64 v160, 0, v160, s[0:1]
	v_cndmask_b32_e64 v200, v200, 0, s[0:1]
	v_cndmask_b32_e64 v161, 0, v161, s[2:3]
	v_cndmask_b32_e64 v201, v201, 0, s[2:3]
	v_cndmask_b32_e64 v162, 0, v162, s[4:5]
	v_cndmask_b32_e64 v202, v202, 0, s[4:5]
	v_cndmask_b32_e64 v163, 0, v163, s[6:7]
	v_cndmask_b32_e64 v203, v203, 0, s[6:7]
	ds_write_b128 v7, v[160:163]
	v_cvt_pk_bf16_f32 v204, v160, v161
	v_cvt_pk_bf16_f32 v205, v162, v163
	ds_write_b16 v9, v204
	ds_write_b16_d16_hi v9, v204 offset:144
	ds_write_b16 v9, v205 offset:288
	ds_write_b16_d16_hi v9, v205 offset:432
	v_cvt_pk_bf16_f32 v200, v200, v201
	v_cvt_pk_bf16_f32 v201, v202, v203
	global_store_dwordx2 v10, v[200:201], s[26:27]
	v_sub_f32_e32 v70, v60, v69
	v_sub_f32_e32 v164, v69, v60
	v_sub_f32_e32 v71, v61, v69
	v_sub_f32_e32 v165, v69, v61
	v_sub_f32_e32 v72, v62, v69
	v_sub_f32_e32 v180, v69, v62
	v_sub_f32_e32 v73, v63, v69
	v_sub_f32_e32 v181, v69, v63
	v_mul_f32_e32 v70, 0x3fb8aa3b, v70
	v_mul_f32_e32 v164, 0x3fb8aa3b, v164
	v_mul_f32_e32 v71, 0x3fb8aa3b, v71
	v_mul_f32_e32 v165, 0x3fb8aa3b, v165
	v_mul_f32_e32 v72, 0x3fb8aa3b, v72
	v_mul_f32_e32 v180, 0x3fb8aa3b, v180
	v_mul_f32_e32 v73, 0x3fb8aa3b, v73
	v_mul_f32_e32 v181, 0x3fb8aa3b, v181
	v_exp_f32_e32 v70, v70
	v_exp_f32_e32 v164, v164
	v_exp_f32_e32 v71, v71
	v_exp_f32_e32 v165, v165
	v_exp_f32_e32 v72, v72
	v_exp_f32_e32 v180, v180
	v_exp_f32_e32 v73, v73
	v_exp_f32_e32 v181, v181
	v_mul_f32_e32 v234, v234, v70
	v_mul_f32_e32 v238, v238, v164
	v_mul_f32_e32 v235, v235, v71
	v_mul_f32_e32 v239, v239, v165
	v_mul_f32_e32 v236, v236, v72
	v_mul_f32_e32 v240, v240, v180
	v_mul_f32_e32 v237, v237, v73
	v_mul_f32_e32 v241, v241, v181
	v_mul_f32_e32 v234, v64, v234
	v_mul_f32_e32 v235, v65, v235
	v_mul_f32_e32 v236, v66, v236
	v_mul_f32_e32 v237, v67, v237
	v_cndmask_b32_e64 v234, 0, v234, s[28:29]
	v_cndmask_b32_e64 v238, v238, 0, s[28:29]
	v_cndmask_b32_e64 v235, 0, v235, s[30:31]
	v_cndmask_b32_e64 v239, v239, 0, s[30:31]
	v_cndmask_b32_e64 v236, 0, v236, s[32:33]
	v_cndmask_b32_e64 v240, v240, 0, s[32:33]
	v_cndmask_b32_e64 v237, 0, v237, s[34:35]
	v_cndmask_b32_e64 v241, v241, 0, s[34:35]
	ds_write_b128 v7, v[234:237] offset:4352
	v_cvt_pk_bf16_f32 v246, v234, v235
	v_cvt_pk_bf16_f32 v247, v236, v237
	ds_write_b16 v9, v246 offset:32
	ds_write_b16_d16_hi v9, v246 offset:176
	ds_write_b16 v9, v247 offset:320
	ds_write_b16_d16_hi v9, v247 offset:464
	v_cvt_pk_bf16_f32 v238, v238, v239
	v_cvt_pk_bf16_f32 v239, v240, v241
	global_store_dwordx2 v10, v[238:239], s[26:27] offset:2048
	s_waitcnt lgkmcnt(0)
	s_barrier
	v_readfirstlane_b32 s26, v135
	s_lshr_b32 s26, s26, 6
	s_cmp_eq_u32 s26, 0
	s_cbranch_scc1 .Lpd_inv
	s_cmp_lt_u32 s26, 4
	s_cbranch_scc1 .Lpd_done
	s_lshr_b32 s27, s26, 1
	s_and_b32 s27, s27, 1
	s_and_b32 s28, s26, 1
	s_lshl_b32 s28, s28, 6
	v_and_b32_e32 v4, 63, v135
	v_add_u32_e32 v5, s28, v4
	s_mul_i32 s29, s27, 0x2200
	v_lshl_add_u32 v6, v5, 1, s29
	s_lshl_b32 s30, s27, 7
	s_add_u32 s30, s30, s25
	v_and_b32_e32 v7, 31, v135
	v_lshl_add_u32 v7, v7, 2, s30
	v_mov_b32_e32 v9, s25
	ds_read_b32 v10, v7
	ds_read_b32 v11, v9 offset:252
	ds_read_u16 v136, v6
	ds_read_u16 v137, v6 offset:272
	ds_read_u16 v138, v6 offset:544
	ds_read_u16 v139, v6 offset:816
	ds_read_u16 v140, v6 offset:1088
	ds_read_u16 v141, v6 offset:1360
	ds_read_u16 v142, v6 offset:1632
	ds_read_u16 v143, v6 offset:1904
	ds_read_u16 v144, v6 offset:2176
	ds_read_u16 v145, v6 offset:2448
	ds_read_u16 v146, v6 offset:2720
	ds_read_u16 v147, v6 offset:2992
	ds_read_u16 v148, v6 offset:3264
	ds_read_u16 v149, v6 offset:3536
	ds_read_u16 v150, v6 offset:3808
	ds_read_u16 v151, v6 offset:4080
	ds_read_u16 v184, v6 offset:4352
	ds_read_u16 v185, v6 offset:4624
	ds_read_u16 v186, v6 offset:4896
	ds_read_u16 v187, v6 offset:5168
	ds_read_u16 v188, v6 offset:5440
	ds_read_u16 v189, v6 offset:5712
	ds_read_u16 v190, v6 offset:5984
	ds_read_u16 v191, v6 offset:6256
	ds_read_u16 v192, v6 offset:6528
	ds_read_u16 v193, v6 offset:6800
	ds_read_u16 v194, v6 offset:7072
	ds_read_u16 v195, v6 offset:7344
	ds_read_u16 v196, v6 offset:7616
	ds_read_u16 v197, v6 offset:7888
	ds_read_u16 v198, v6 offset:8160
	ds_read_u16 v199, v6 offset:8432
	v_lshrrev_b32_e32 v2, 4, v5
	v_lshl_add_u32 v2, v2, 1, s27
	v_lshlrev_b32_e32 v2, 10, v2
	v_and_b32_e32 v3, 15, v5
	v_lshl_add_u32 v2, v3, 4, v2
	s_add_u32 s4, s10, s16
	s_addc_u32 s5, s11, s17
	s_add_u32 s4, s4, 0x15800000
	s_addc_u32 s5, s5, 0
	s_waitcnt lgkmcnt(14)
	v_sub_f32_e32 v10, v11, v10
	v_mul_f32_e32 v10, 0x3fb8aa3b, v10
	v_exp_f32_e32 v10, v10
	s_nop 1
	s_waitcnt lgkmcnt(14)
	v_readlane_b32 s32, v10, 0
	v_readlane_b32 s33, v10, 1
	v_readlane_b32 s34, v10, 2
	v_readlane_b32 s35, v10, 3
	v_readlane_b32 s36, v10, 4
	v_readlane_b32 s37, v10, 5
	v_readlane_b32 s38, v10, 6
	v_readlane_b32 s39, v10, 7
	v_lshlrev_b32_e32 v136, 16, v136
	v_lshlrev_b32_e32 v137, 16, v137
	v_lshlrev_b32_e32 v138, 16, v138
	v_lshlrev_b32_e32 v139, 16, v139
	v_lshlrev_b32_e32 v140, 16, v140
	v_lshlrev_b32_e32 v141, 16, v141
	v_lshlrev_b32_e32 v142, 16, v142
	v_lshlrev_b32_e32 v143, 16, v143
	v_mul_f32_e32 v136, s32, v136
	v_mul_f32_e32 v137, s33, v137
	v_mul_f32_e32 v138, s34, v138
	v_mul_f32_e32 v139, s35, v139
	v_mul_f32_e32 v140, s36, v140
	v_mul_f32_e32 v141, s37, v141
	v_mul_f32_e32 v142, s38, v142
	v_mul_f32_e32 v143, s39, v143
	v_cvt_pk_bf16_f32 v12, v136, v137
	v_cvt_pk_bf16_f32 v13, v138, v139
	v_cvt_pk_bf16_f32 v14, v140, v141
	v_cvt_pk_bf16_f32 v15, v142, v143
	global_store_dwordx4 v2, v[12:15], s[4:5]
	s_waitcnt lgkmcnt(14)
	v_readlane_b32 s32, v10, 8
	v_readlane_b32 s33, v10, 9
	v_readlane_b32 s34, v10, 10
	v_readlane_b32 s35, v10, 11
	v_readlane_b32 s36, v10, 12
	v_readlane_b32 s37, v10, 13
	v_readlane_b32 s38, v10, 14
	v_readlane_b32 s39, v10, 15
	v_lshlrev_b32_e32 v144, 16, v144
	v_lshlrev_b32_e32 v145, 16, v145
	v_lshlrev_b32_e32 v146, 16, v146
	v_lshlrev_b32_e32 v147, 16, v147
	v_lshlrev_b32_e32 v148, 16, v148
	v_lshlrev_b32_e32 v149, 16, v149
	v_lshlrev_b32_e32 v150, 16, v150
	v_lshlrev_b32_e32 v151, 16, v151
	v_mul_f32_e32 v144, s32, v144
	v_mul_f32_e32 v145, s33, v145
	v_mul_f32_e32 v146, s34, v146
	v_mul_f32_e32 v147, s35, v147
	v_mul_f32_e32 v148, s36, v148
	v_mul_f32_e32 v149, s37, v149
	v_mul_f32_e32 v150, s38, v150
	v_mul_f32_e32 v151, s39, v151
	v_cvt_pk_bf16_f32 v16, v144, v145
	v_cvt_pk_bf16_f32 v17, v146, v147
	v_cvt_pk_bf16_f32 v18, v148, v149
	v_cvt_pk_bf16_f32 v19, v150, v151
	global_store_dwordx4 v2, v[16:19], s[4:5] offset:256
	s_waitcnt lgkmcnt(8)
	v_readlane_b32 s32, v10, 16
	v_readlane_b32 s33, v10, 17
	v_readlane_b32 s34, v10, 18
	v_readlane_b32 s35, v10, 19
	v_readlane_b32 s36, v10, 20
	v_readlane_b32 s37, v10, 21
	v_readlane_b32 s38, v10, 22
	v_readlane_b32 s39, v10, 23
	v_lshlrev_b32_e32 v184, 16, v184
	v_lshlrev_b32_e32 v185, 16, v185
	v_lshlrev_b32_e32 v186, 16, v186
	v_lshlrev_b32_e32 v187, 16, v187
	v_lshlrev_b32_e32 v188, 16, v188
	v_lshlrev_b32_e32 v189, 16, v189
	v_lshlrev_b32_e32 v190, 16, v190
	v_lshlrev_b32_e32 v191, 16, v191
	v_mul_f32_e32 v184, s32, v184
	v_mul_f32_e32 v185, s33, v185
	v_mul_f32_e32 v186, s34, v186
	v_mul_f32_e32 v187, s35, v187
	v_mul_f32_e32 v188, s36, v188
	v_mul_f32_e32 v189, s37, v189
	v_mul_f32_e32 v190, s38, v190
	v_mul_f32_e32 v191, s39, v191
	v_cvt_pk_bf16_f32 v12, v184, v185
	v_cvt_pk_bf16_f32 v13, v186, v187
	v_cvt_pk_bf16_f32 v14, v188, v189
	v_cvt_pk_bf16_f32 v15, v190, v191
	global_store_dwordx4 v2, v[12:15], s[4:5] offset:512
	s_waitcnt lgkmcnt(0)
	v_readlane_b32 s32, v10, 24
	v_readlane_b32 s33, v10, 25
	v_readlane_b32 s34, v10, 26
	v_readlane_b32 s35, v10, 27
	v_readlane_b32 s36, v10, 28
	v_readlane_b32 s37, v10, 29
	v_readlane_b32 s38, v10, 30
	v_readlane_b32 s39, v10, 31
	v_lshlrev_b32_e32 v192, 16, v192
	v_lshlrev_b32_e32 v193, 16, v193
	v_lshlrev_b32_e32 v194, 16, v194
	v_lshlrev_b32_e32 v195, 16, v195
	v_lshlrev_b32_e32 v196, 16, v196
	v_lshlrev_b32_e32 v197, 16, v197
	v_lshlrev_b32_e32 v198, 16, v198
	v_lshlrev_b32_e32 v199, 16, v199
	v_mul_f32_e32 v192, s32, v192
	v_mul_f32_e32 v193, s33, v193
	v_mul_f32_e32 v194, s34, v194
	v_mul_f32_e32 v195, s35, v195
	v_mul_f32_e32 v196, s36, v196
	v_mul_f32_e32 v197, s37, v197
	v_mul_f32_e32 v198, s38, v198
	v_mul_f32_e32 v199, s39, v199
	v_cvt_pk_bf16_f32 v16, v192, v193
	v_cvt_pk_bf16_f32 v17, v194, v195
	v_cvt_pk_bf16_f32 v18, v196, v197
	v_cvt_pk_bf16_f32 v19, v198, v199
	global_store_dwordx4 v2, v[16:19], s[4:5] offset:768
	s_branch .Lpd_done

.Lpd_done:
	s_waitcnt lgkmcnt(0)
	s_barrier
	s_ashr_i32 s6, s24, 6
	v_and_b32_e32 v1, 15, v134
	v_lshrrev_b32_e32 v3, 4, v134
	v_lshlrev_b32_e32 v4, 5, v1
	v_lshl_add_u32 v4, v3, 3, v4
	v_add_u32_e32 v4, 0x1c400, v4
	v_mul_u32_u24_e32 v5, 0x90, v1
	v_lshl_add_u32 v5, v3, 3, v5
	v_add_u32_e32 v5, 0x11000, v5
	v_lshlrev_b32_e32 v7, 4, v3
	v_add_u32_e32 v7, 0x20500, v7
	s_cmp_gt_i32 s6, 3
	s_cbranch_scc1 .Lpe_w
	s_lshl_b32 s1, s6, 6
	v_mul_u32_u24_e32 v6, 0x440, v3
	v_lshl_add_u32 v6, v1, 1, v6
	v_add_u32_e32 v6, s1, v6
	s_lshl_b32 s1, s6, 12
	v_lshl_add_u32 v9, v134, 3, s1
	s_add_u32 s4, s10, s16
	s_addc_u32 s5, s11, s17
	s_add_u32 s4, s4, 0x17800000
	s_addc_u32 s5, s5, 0
	ds_read_b128 v[10:13], v7 offset:256
	ds_read_u16 v14, v6 offset:34816
	ds_read_u16 v15, v6 offset:35088
	ds_read_u16 v16, v6 offset:35360
	ds_read_u16 v17, v6 offset:35632
	ds_read_u16 v18, v6 offset:34848
	ds_read_u16 v19, v6 offset:35120
	ds_read_u16 v20, v6 offset:35392
	ds_read_u16 v21, v6 offset:35664
	ds_read_b64 v[164:165], v4 offset:0
	ds_read_b128 v[22:25], v7 offset:320
	ds_read_u16 v136, v6 offset:39168
	ds_read_u16 v137, v6 offset:39440
	ds_read_u16 v138, v6 offset:39712
	ds_read_u16 v139, v6 offset:39984
	ds_read_u16 v140, v6 offset:39200
	ds_read_u16 v141, v6 offset:39472
	ds_read_u16 v142, v6 offset:39744
	ds_read_u16 v143, v6 offset:40016
	ds_read_b64 v[180:181], v5 offset:2304
	ds_read_b64 v[204:205], v4 offset:512
	s_waitcnt lgkmcnt(11)
	v_lshlrev_b32_e32 v14, 16, v14
	v_lshlrev_b32_e32 v15, 16, v15
	v_lshlrev_b32_e32 v16, 16, v16
	v_lshlrev_b32_e32 v17, 16, v17
	v_lshlrev_b32_e32 v18, 16, v18
	v_lshlrev_b32_e32 v19, 16, v19
	v_lshlrev_b32_e32 v20, 16, v20
	v_lshlrev_b32_e32 v21, 16, v21
	v_mul_f32_e32 v14, v10, v14
	v_mul_f32_e32 v15, v11, v15
	v_mul_f32_e32 v16, v12, v16
	v_mul_f32_e32 v17, v13, v17
	v_mul_f32_e32 v18, v10, v18
	v_mul_f32_e32 v19, v11, v19
	v_mul_f32_e32 v20, v12, v20
	v_mul_f32_e32 v21, v13, v21
	v_cvt_pk_bf16_f32 v246, v14, v15
	v_cvt_pk_bf16_f32 v247, v16, v17
	v_cvt_pk_bf16_f32 v144, v18, v19
	v_cvt_pk_bf16_f32 v145, v20, v21
	v_mfma_f32_16x16x16_bf16 v[14:17], v[164:165], v[246:247], 0
	s_nop 0
	v_mfma_f32_16x16x16_bf16 v[18:21], v[164:165], v[144:145], 0
	ds_read_b128 v[148:151], v7 offset:384
	ds_read_u16 v160, v6 offset:43520
	ds_read_u16 v161, v6 offset:43792
	ds_read_u16 v162, v6 offset:44064
	ds_read_u16 v163, v6 offset:44336
	ds_read_u16 v168, v6 offset:43552
	ds_read_u16 v169, v6 offset:43824
	ds_read_u16 v170, v6 offset:44096
	ds_read_u16 v171, v6 offset:44368
	ds_read_b64 v[146:147], v5 offset:4608
	ds_read_b64 v[172:173], v5 offset:4640
	ds_read_b64 v[174:175], v4 offset:1024
	v_cvt_pk_bf16_f32 v176, v14, v15
	v_cvt_pk_bf16_f32 v177, v16, v17
	global_store_dwordx2 v9, v[176:177], s[4:5] offset:0
	v_cvt_pk_bf16_f32 v178, v18, v19
	v_cvt_pk_bf16_f32 v179, v20, v21
	global_store_dwordx2 v9, v[178:179], s[4:5] offset:2048
	s_waitcnt lgkmcnt(13)
	v_mfma_f32_16x16x16_bf16 v[184:187], v[180:181], v[176:177], 0
	v_mfma_f32_16x16x16_bf16 v[188:191], v[180:181], v[178:179], 0
	s_waitcnt lgkmcnt(12)
	v_lshlrev_b32_e32 v136, 16, v136
	v_lshlrev_b32_e32 v137, 16, v137
	v_lshlrev_b32_e32 v138, 16, v138
	v_lshlrev_b32_e32 v139, 16, v139
	v_lshlrev_b32_e32 v140, 16, v140
	v_lshlrev_b32_e32 v141, 16, v141
	v_lshlrev_b32_e32 v142, 16, v142
	v_lshlrev_b32_e32 v143, 16, v143
	v_mul_f32_e32 v136, v22, v136
	v_mul_f32_e32 v137, v23, v137
	v_mul_f32_e32 v138, v24, v138
	v_mul_f32_e32 v139, v25, v139
	v_mul_f32_e32 v140, v22, v140
	v_mul_f32_e32 v141, v23, v141
	v_mul_f32_e32 v142, v24, v142
	v_mul_f32_e32 v143, v25, v143
	v_sub_f32_e32 v184, v136, v184
	v_sub_f32_e32 v185, v137, v185
	v_sub_f32_e32 v186, v138, v186
	v_sub_f32_e32 v187, v139, v187
	v_cvt_pk_bf16_f32 v246, v184, v185
	v_cvt_pk_bf16_f32 v247, v186, v187
	v_sub_f32_e32 v188, v140, v188
	v_sub_f32_e32 v189, v141, v189
	v_sub_f32_e32 v190, v142, v190
	v_sub_f32_e32 v191, v143, v191
	v_cvt_pk_bf16_f32 v144, v188, v189
	v_cvt_pk_bf16_f32 v145, v190, v191
	v_mfma_f32_16x16x16_bf16 v[184:187], v[204:205], v[246:247], 0
	s_nop 0
	v_mfma_f32_16x16x16_bf16 v[188:191], v[204:205], v[144:145], 0
	ds_read_b128 v[192:195], v7 offset:448
	ds_read_u16 v196, v6 offset:47872
	ds_read_u16 v197, v6 offset:48144
	ds_read_u16 v198, v6 offset:48416
	ds_read_u16 v199, v6 offset:48688
	ds_read_u16 v200, v6 offset:47904
	ds_read_u16 v201, v6 offset:48176
	ds_read_u16 v202, v6 offset:48448
	ds_read_u16 v203, v6 offset:48720
	ds_read_b64 v[164:165], v5 offset:6912
	ds_read_b64 v[180:181], v5 offset:6944
	ds_read_b64 v[234:235], v5 offset:6976
	ds_read_b64 v[236:237], v4 offset:1536
	v_cvt_pk_bf16_f32 v238, v184, v185
	v_cvt_pk_bf16_f32 v239, v186, v187
	global_store_dwordx2 v9, v[238:239], s[4:5] offset:512
	v_cvt_pk_bf16_f32 v240, v188, v189
	v_cvt_pk_bf16_f32 v241, v190, v191
	global_store_dwordx2 v9, v[240:241], s[4:5] offset:2560
	s_waitcnt lgkmcnt(14)
	v_mfma_f32_16x16x16_bf16 v[10:13], v[146:147], v[176:177], 0
	v_mfma_f32_16x16x16_bf16 v[14:17], v[146:147], v[178:179], 0
	v_mfma_f32_16x16x16_bf16 v[10:13], v[172:173], v[238:239], v[10:13]
	v_mfma_f32_16x16x16_bf16 v[14:17], v[172:173], v[240:241], v[14:17]
	s_waitcnt lgkmcnt(13)
	v_lshlrev_b32_e32 v160, 16, v160
	v_lshlrev_b32_e32 v161, 16, v161
	v_lshlrev_b32_e32 v162, 16, v162
	v_lshlrev_b32_e32 v163, 16, v163
	v_lshlrev_b32_e32 v168, 16, v168
	v_lshlrev_b32_e32 v169, 16, v169
	v_lshlrev_b32_e32 v170, 16, v170
	v_lshlrev_b32_e32 v171, 16, v171
	v_mul_f32_e32 v160, v148, v160
	v_mul_f32_e32 v161, v149, v161
	v_mul_f32_e32 v162, v150, v162
	v_mul_f32_e32 v163, v151, v163
	v_mul_f32_e32 v168, v148, v168
	v_mul_f32_e32 v169, v149, v169
	v_mul_f32_e32 v170, v150, v170
	v_mul_f32_e32 v171, v151, v171
	v_sub_f32_e32 v10, v160, v10
	v_sub_f32_e32 v11, v161, v11
	v_sub_f32_e32 v12, v162, v12
	v_sub_f32_e32 v13, v163, v13
	v_cvt_pk_bf16_f32 v246, v10, v11
	v_cvt_pk_bf16_f32 v247, v12, v13
	v_sub_f32_e32 v14, v168, v14
	v_sub_f32_e32 v15, v169, v15
	v_sub_f32_e32 v16, v170, v16
	v_sub_f32_e32 v17, v171, v17
	v_cvt_pk_bf16_f32 v144, v14, v15
	v_cvt_pk_bf16_f32 v145, v16, v17
	v_mfma_f32_16x16x16_bf16 v[10:13], v[174:175], v[246:247], 0
	s_nop 0
	v_mfma_f32_16x16x16_bf16 v[14:17], v[174:175], v[144:145], 0
	s_nop 5
	v_cvt_pk_bf16_f32 v204, v10, v11
	v_cvt_pk_bf16_f32 v205, v12, v13
	global_store_dwordx2 v9, v[204:205], s[4:5] offset:1024
	v_cvt_pk_bf16_f32 v146, v14, v15
	v_cvt_pk_bf16_f32 v147, v16, v17
	global_store_dwordx2 v9, v[146:147], s[4:5] offset:3072
	s_waitcnt lgkmcnt(1)
	v_mfma_f32_16x16x16_bf16 v[18:21], v[164:165], v[176:177], 0
	v_mfma_f32_16x16x16_bf16 v[22:25], v[164:165], v[178:179], 0
	v_mfma_f32_16x16x16_bf16 v[18:21], v[180:181], v[238:239], v[18:21]
	v_mfma_f32_16x16x16_bf16 v[22:25], v[180:181], v[240:241], v[22:25]
	v_mfma_f32_16x16x16_bf16 v[18:21], v[234:235], v[204:205], v[18:21]
	v_mfma_f32_16x16x16_bf16 v[22:25], v[234:235], v[146:147], v[22:25]
	s_waitcnt lgkmcnt(0)
	v_lshlrev_b32_e32 v196, 16, v196
	v_lshlrev_b32_e32 v197, 16, v197
	v_lshlrev_b32_e32 v198, 16, v198
	v_lshlrev_b32_e32 v199, 16, v199
	v_lshlrev_b32_e32 v200, 16, v200
	v_lshlrev_b32_e32 v201, 16, v201
	v_lshlrev_b32_e32 v202, 16, v202
	v_lshlrev_b32_e32 v203, 16, v203
	v_mul_f32_e32 v196, v192, v196
	v_mul_f32_e32 v197, v193, v197
	v_mul_f32_e32 v198, v194, v198
	v_mul_f32_e32 v199, v195, v199
	v_mul_f32_e32 v200, v192, v200
	v_mul_f32_e32 v201, v193, v201
	v_mul_f32_e32 v202, v194, v202
	v_mul_f32_e32 v203, v195, v203
	v_sub_f32_e32 v18, v196, v18
	v_sub_f32_e32 v19, v197, v19
	v_sub_f32_e32 v20, v198, v20
	v_sub_f32_e32 v21, v199, v21
	v_cvt_pk_bf16_f32 v172, v18, v19
	v_cvt_pk_bf16_f32 v173, v20, v21
	v_sub_f32_e32 v22, v200, v22
	v_sub_f32_e32 v23, v201, v23
	v_sub_f32_e32 v24, v202, v24
	v_sub_f32_e32 v25, v203, v25
	v_cvt_pk_bf16_f32 v246, v22, v23
	v_cvt_pk_bf16_f32 v247, v24, v25
	v_mfma_f32_16x16x16_bf16 v[18:21], v[236:237], v[172:173], 0
	s_nop 0
	v_mfma_f32_16x16x16_bf16 v[22:25], v[236:237], v[246:247], 0
	s_nop 5
	v_cvt_pk_bf16_f32 v144, v18, v19
	v_cvt_pk_bf16_f32 v145, v20, v21
	global_store_dwordx2 v9, v[144:145], s[4:5] offset:1536
	v_cvt_pk_bf16_f32 v174, v22, v23
	v_cvt_pk_bf16_f32 v175, v24, v25
	global_store_dwordx2 v9, v[174:175], s[4:5] offset:3584
	s_branch .Lpe_done
